# layer-0 post phase (both sites + narrow GEMM) hand-written with batched loads; norm0 rows batched; counted waits now count loads only
# speedup vs baseline: 1.0288x; 1.0214x over previous
; DI int osgpr(int v) { asm volatile("" : "+s"(v)); return v; }
; DI void norm0_phase(const P& p, unsigned char* smem) {
;     ...
;     for (int rt = osgpr(blockIdx.x); rt < NROW / 16; rt += gridDim.x) {
;       for (int rr = 0; rr < 2; ++rr) {
;         const int row = rt * 16 + wave * 2 + rr;
;         const float* h = row < NLAT ? p.x + (size_t)row * DM : p.ctx + (size_t)(row - NLAT) * DM;
;         const int mr = row < NLAT ? (row >> 11) : 4;
;         f32x4 v[8]; float ss = 0.f;
; #pragma unroll
;         for (int i = 0; i < 8; ++i) { v[i] = __builtin_nontemporal_load((const f32x4*)(h + i * 256 + lane * 4)); ss += v[i][0] * v[i][0] + v[i][1] * v[i][1] + v[i][2] * v[i][2] + v[i][3] * v[i][3]; }
;         ss = wave_sum(ss);
;         const float rstd = rsqrtf(ss * (1.f / 2048.f) + 1e-6f);
;         const float* md = mod + (size_t)mr * 6144;
; #pragma unroll
;         for (int i = 0; i < 8; ++i) {
;             const int j = i * 256 + lane * 4;
;             const f32x4 gw = *(const f32x4*)(p.norm_pre + j), sh = *(const f32x4*)(md + j), scl = *(const f32x4*)(md + 2048 + j);
;             float o[4];
; #pragma unroll
;             for (int e = 0; e < 4; ++e) o[e] = v[i][e] * rstd * gw[e] * (1.f + scl[e]) + sh[e];
;             u32x2 w; w.x = pk2(o[0], o[1]); w.y = pk2(o[2], o[3]);
;             *(u32x2*)(nb + (size_t)row * DM + j) = w;
.LBB0_97:
	s_lshl_b32 s24, s28, 4
	v_add_u32_e32 v79, s24, v69
	v_ashrrev_i32_e32 v0, 11, v79
	v_mul_hi_i32_i24_e32 v61, 0x6000, v0
	v_mul_i32_i24_e32 v60, 0x6000, v0
	s_mov_b64 s[18:19], -1
	v_and_b32_e32 v4, 63, v166
	v_readfirstlane_b32 s20, v69
	v_lshlrev_b32_e32 v0, 4, v4
	v_lshlrev_b32_e32 v2, 3, v4
	v_add_u32_e32 v1, 0x1000, v0
	v_add_u32_e32 v3, 0x1000, v2
	s_add_u32 s20, s24, s20
	s_sub_u32 s23, s20, 0x2000
	s_lshr_b32 s25, s20, 11
	s_cmpk_ge_u32 s20, 0x2000
	s_cselect_b32 s44, s90, s92
	s_cselect_b32 s45, s91, s93
	s_cselect_b32 s23, s23, s20
	s_cselect_b32 s25, 4, s25
	s_lshl_b32 s23, s23, 13
	s_add_u32 s44, s44, s23
	s_addc_u32 s45, s45, 0
	s_add_u32 s46, s44, 0x2000
	s_addc_u32 s47, s45, 0
	s_mul_i32 s25, s25, 0x6000
	s_add_u32 s22, s8, s25
	s_addc_u32 s23, s9, 0
	s_add_u32 s48, s22, 0x2000
	s_addc_u32 s49, s23, 0
	s_lshl_b32 s25, s20, 12
	s_add_u32 s26, s10, s25
	s_addc_u32 s27, s11, 0
	global_load_dwordx4 v[80:83], v0, s[6:7] offset:0
	global_load_dwordx4 v[84:87], v0, s[6:7] offset:1024
	global_load_dwordx4 v[88:91], v0, s[6:7] offset:2048
	global_load_dwordx4 v[92:95], v0, s[6:7] offset:3072
	global_load_dwordx4 v[96:99], v1, s[6:7] offset:0
	global_load_dwordx4 v[100:103], v1, s[6:7] offset:1024
	global_load_dwordx4 v[104:107], v1, s[6:7] offset:2048
	global_load_dwordx4 v[108:111], v1, s[6:7] offset:3072
	global_load_dwordx4 v[112:115], v0, s[44:45] offset:0 nt
	global_load_dwordx4 v[116:119], v0, s[44:45] offset:1024 nt
	global_load_dwordx4 v[120:123], v0, s[44:45] offset:2048 nt
	global_load_dwordx4 v[124:127], v0, s[44:45] offset:3072 nt
	global_load_dwordx4 v[128:131], v1, s[44:45] offset:0 nt
	global_load_dwordx4 v[132:135], v1, s[44:45] offset:1024 nt
	global_load_dwordx4 v[136:139], v1, s[44:45] offset:2048 nt
	global_load_dwordx4 v[140:143], v1, s[44:45] offset:3072 nt
	global_load_dwordx4 v[144:147], v0, s[46:47] offset:0 nt
	global_load_dwordx4 v[148:151], v0, s[46:47] offset:1024 nt
	global_load_dwordx4 v[152:155], v0, s[46:47] offset:2048 nt
	global_load_dwordx4 v[156:159], v0, s[46:47] offset:3072 nt
	global_load_dwordx4 v[160:163], v1, s[46:47] offset:0 nt
	global_load_dwordx4 v[232:235], v1, s[46:47] offset:1024 nt
	global_load_dwordx4 v[236:239], v1, s[46:47] offset:2048 nt
	global_load_dwordx4 v[240:243], v1, s[46:47] offset:3072 nt
	global_load_dwordx4 v[168:171], v0, s[22:23] offset:0
	global_load_dwordx4 v[200:203], v0, s[48:49] offset:0
	global_load_dwordx4 v[172:175], v0, s[22:23] offset:1024
	global_load_dwordx4 v[204:207], v0, s[48:49] offset:1024
	global_load_dwordx4 v[176:179], v0, s[22:23] offset:2048
	global_load_dwordx4 v[208:211], v0, s[48:49] offset:2048
	global_load_dwordx4 v[180:183], v0, s[22:23] offset:3072
	global_load_dwordx4 v[212:215], v0, s[48:49] offset:3072
	global_load_dwordx4 v[184:187], v1, s[22:23] offset:0
	global_load_dwordx4 v[216:219], v1, s[48:49] offset:0
	global_load_dwordx4 v[188:191], v1, s[22:23] offset:1024
	global_load_dwordx4 v[220:223], v1, s[48:49] offset:1024
	global_load_dwordx4 v[192:195], v1, s[22:23] offset:2048
	global_load_dwordx4 v[224:227], v1, s[48:49] offset:2048
	global_load_dwordx4 v[196:199], v1, s[22:23] offset:3072
	global_load_dwordx4 v[228:231], v1, s[48:49] offset:3072
	s_waitcnt vmcnt(16)
	v_mul_f32_e32 v4, v112, v112
	v_mul_f32_e32 v5, v113, v113
	v_fmac_f32_e32 v4, v114, v114
	v_fmac_f32_e32 v5, v115, v115
	v_fmac_f32_e32 v4, v116, v116
	v_fmac_f32_e32 v5, v117, v117
	v_fmac_f32_e32 v4, v118, v118
	v_fmac_f32_e32 v5, v119, v119
	v_fmac_f32_e32 v4, v120, v120
	v_fmac_f32_e32 v5, v121, v121
	v_fmac_f32_e32 v4, v122, v122
	v_fmac_f32_e32 v5, v123, v123
	v_fmac_f32_e32 v4, v124, v124
	v_fmac_f32_e32 v5, v125, v125
	v_fmac_f32_e32 v4, v126, v126
	v_fmac_f32_e32 v5, v127, v127
	v_fmac_f32_e32 v4, v128, v128
	v_fmac_f32_e32 v5, v129, v129
	v_fmac_f32_e32 v4, v130, v130
	v_fmac_f32_e32 v5, v131, v131
	v_fmac_f32_e32 v4, v132, v132
	v_fmac_f32_e32 v5, v133, v133
	v_fmac_f32_e32 v4, v134, v134
	v_fmac_f32_e32 v5, v135, v135
	v_fmac_f32_e32 v4, v136, v136
	v_fmac_f32_e32 v5, v137, v137
	v_fmac_f32_e32 v4, v138, v138
	v_fmac_f32_e32 v5, v139, v139
	v_fmac_f32_e32 v4, v140, v140
	v_fmac_f32_e32 v5, v141, v141
	v_fmac_f32_e32 v4, v142, v142
	v_fmac_f32_e32 v5, v143, v143
	v_add_f32_e32 v4, v4, v5
	v_mul_f32_e32 v6, v144, v144
	v_mul_f32_e32 v7, v145, v145
	v_fmac_f32_e32 v6, v146, v146
	v_fmac_f32_e32 v7, v147, v147
	v_fmac_f32_e32 v6, v148, v148
	v_fmac_f32_e32 v7, v149, v149
	v_fmac_f32_e32 v6, v150, v150
	v_fmac_f32_e32 v7, v151, v151
	v_fmac_f32_e32 v6, v152, v152
	v_fmac_f32_e32 v7, v153, v153
	v_fmac_f32_e32 v6, v154, v154
	v_fmac_f32_e32 v7, v155, v155
	v_fmac_f32_e32 v6, v156, v156
	v_fmac_f32_e32 v7, v157, v157
	v_fmac_f32_e32 v6, v158, v158
	v_fmac_f32_e32 v7, v159, v159
	v_fmac_f32_e32 v6, v160, v160
	v_fmac_f32_e32 v7, v161, v161
	v_fmac_f32_e32 v6, v162, v162
	v_fmac_f32_e32 v7, v163, v163
	v_fmac_f32_e32 v6, v232, v232
	v_fmac_f32_e32 v7, v233, v233
	v_fmac_f32_e32 v6, v234, v234
	v_fmac_f32_e32 v7, v235, v235
	v_fmac_f32_e32 v6, v236, v236
	v_fmac_f32_e32 v7, v237, v237
	v_fmac_f32_e32 v6, v238, v238
	v_fmac_f32_e32 v7, v239, v239
	v_fmac_f32_e32 v6, v240, v240
	v_fmac_f32_e32 v7, v241, v241
	v_fmac_f32_e32 v6, v242, v242
	v_fmac_f32_e32 v7, v243, v243
	v_add_f32_e32 v6, v6, v7
	ds_bpermute_b32 v8, v72, v4
	ds_bpermute_b32 v9, v72, v6
	s_waitcnt lgkmcnt(1)
	v_add_f32_e32 v4, v4, v8
	s_waitcnt lgkmcnt(0)
	v_add_f32_e32 v6, v6, v9
	ds_bpermute_b32 v8, v73, v4
	ds_bpermute_b32 v9, v73, v6
	s_waitcnt lgkmcnt(1)
	v_add_f32_e32 v4, v4, v8
	s_waitcnt lgkmcnt(0)
	v_add_f32_e32 v6, v6, v9
	ds_bpermute_b32 v8, v74, v4
	ds_bpermute_b32 v9, v74, v6
	s_waitcnt lgkmcnt(1)
; DI void norm0_phase(const P& p, unsigned char* smem) {
;     ...
;         for (int i = 0; i < 8; ++i) { v[i] = __builtin_nontemporal_load((const f32x4*)(h + i * 256 + lane * 4)); ss += v[i][0] * v[i][0] + v[i][1] * v[i][1] + v[i][2] * v[i][2] + v[i][3] * v[i][3]; }
;         ss = wave_sum(ss);
;         const float rstd = rsqrtf(ss * (1.f / 2048.f) + 1e-6f);
;         const float* md = mod + (size_t)mr * 6144;
; #pragma unroll
;         for (int i = 0; i < 8; ++i) {
;             const int j = i * 256 + lane * 4;
;             const f32x4 gw = *(const f32x4*)(p.norm_pre + j), sh = *(const f32x4*)(md + j), scl = *(const f32x4*)(md + 2048 + j);
;             float o[4];
; #pragma unroll
;             for (int e = 0; e < 4; ++e) o[e] = v[i][e] * rstd * gw[e] * (1.f + scl[e]) + sh[e];
;             u32x2 w; w.x = pk2(o[0], o[1]); w.y = pk2(o[2], o[3]);
;             *(u32x2*)(nb + (size_t)row * DM + j) = w;
	v_add_f32_e32 v4, v4, v8
	s_waitcnt lgkmcnt(0)
	v_add_f32_e32 v6, v6, v9
	ds_bpermute_b32 v8, v75, v4
	ds_bpermute_b32 v9, v75, v6
	s_waitcnt lgkmcnt(1)
	v_add_f32_e32 v4, v4, v8
	s_waitcnt lgkmcnt(0)
	v_add_f32_e32 v6, v6, v9
	ds_bpermute_b32 v8, v76, v4
	ds_bpermute_b32 v9, v76, v6
	s_waitcnt lgkmcnt(1)
	v_add_f32_e32 v4, v4, v8
	s_waitcnt lgkmcnt(0)
	v_add_f32_e32 v6, v6, v9
	ds_bpermute_b32 v8, v77, v4
	ds_bpermute_b32 v9, v77, v6
	s_waitcnt lgkmcnt(1)
	v_add_f32_e32 v4, v4, v8
	s_waitcnt lgkmcnt(0)
	v_add_f32_e32 v6, v6, v9
	v_fmamk_f32 v4, v4, 0x3a000000, v78
	v_fmamk_f32 v6, v6, 0x3a000000, v78
	v_rsq_f32_e32 v10, v4
	v_rsq_f32_e32 v11, v6
	s_nop 0
	v_mul_f32_e32 v12, v112, v10
	v_mul_f32_e32 v13, v113, v10
	v_mul_f32_e32 v14, v114, v10
	v_mul_f32_e32 v15, v115, v10
	v_mul_f32_e32 v12, v12, v80
	v_mul_f32_e32 v13, v13, v81
	v_mul_f32_e32 v14, v14, v82
	v_mul_f32_e32 v15, v15, v83
	s_waitcnt vmcnt(14)
	v_add_f32_e32 v16, 1.0, v200
	v_add_f32_e32 v17, 1.0, v201
	v_add_f32_e32 v18, 1.0, v202
	v_add_f32_e32 v19, 1.0, v203
	v_fma_f32 v12, v12, v16, v168
	v_fma_f32 v13, v13, v17, v169
	v_fma_f32 v14, v14, v18, v170
	v_fma_f32 v15, v15, v19, v171
	v_cvt_pk_bf16_f32 v20, v12, v13
	v_cvt_pk_bf16_f32 v21, v14, v15
	global_store_dwordx2 v2, v[20:21], s[26:27] offset:0
	v_mul_f32_e32 v12, v116, v10
	v_mul_f32_e32 v13, v117, v10
	v_mul_f32_e32 v14, v118, v10
	v_mul_f32_e32 v15, v119, v10
	v_mul_f32_e32 v12, v12, v84
	v_mul_f32_e32 v13, v13, v85
	v_mul_f32_e32 v14, v14, v86
	v_mul_f32_e32 v15, v15, v87
	s_waitcnt vmcnt(12)
	v_add_f32_e32 v16, 1.0, v204
	v_add_f32_e32 v17, 1.0, v205
	v_add_f32_e32 v18, 1.0, v206
	v_add_f32_e32 v19, 1.0, v207
	v_fma_f32 v12, v12, v16, v172
	v_fma_f32 v13, v13, v17, v173
	v_fma_f32 v14, v14, v18, v174
	v_fma_f32 v15, v15, v19, v175
	v_cvt_pk_bf16_f32 v22, v12, v13
	v_cvt_pk_bf16_f32 v23, v14, v15
	global_store_dwordx2 v2, v[22:23], s[26:27] offset:512
	v_mul_f32_e32 v12, v120, v10
	v_mul_f32_e32 v13, v121, v10
	v_mul_f32_e32 v14, v122, v10
	v_mul_f32_e32 v15, v123, v10
	v_mul_f32_e32 v12, v12, v88
	v_mul_f32_e32 v13, v13, v89
	v_mul_f32_e32 v14, v14, v90
	v_mul_f32_e32 v15, v15, v91
	s_waitcnt vmcnt(10)
	v_add_f32_e32 v16, 1.0, v208
	v_add_f32_e32 v17, 1.0, v209
	v_add_f32_e32 v18, 1.0, v210
	v_add_f32_e32 v19, 1.0, v211
	v_fma_f32 v12, v12, v16, v176
	v_fma_f32 v13, v13, v17, v177
	v_fma_f32 v14, v14, v18, v178
	v_fma_f32 v15, v15, v19, v179
	v_cvt_pk_bf16_f32 v20, v12, v13
	v_cvt_pk_bf16_f32 v21, v14, v15
	global_store_dwordx2 v2, v[20:21], s[26:27] offset:1024
	v_mul_f32_e32 v12, v124, v10
	v_mul_f32_e32 v13, v125, v10
	v_mul_f32_e32 v14, v126, v10
	v_mul_f32_e32 v15, v127, v10
	v_mul_f32_e32 v12, v12, v92
	v_mul_f32_e32 v13, v13, v93
	v_mul_f32_e32 v14, v14, v94
	v_mul_f32_e32 v15, v15, v95
	s_waitcnt vmcnt(8)
	v_add_f32_e32 v16, 1.0, v212
	v_add_f32_e32 v17, 1.0, v213
	v_add_f32_e32 v18, 1.0, v214
	v_add_f32_e32 v19, 1.0, v215
	v_fma_f32 v12, v12, v16, v180
	v_fma_f32 v13, v13, v17, v181
	v_fma_f32 v14, v14, v18, v182
	v_fma_f32 v15, v15, v19, v183
	v_cvt_pk_bf16_f32 v22, v12, v13
	v_cvt_pk_bf16_f32 v23, v14, v15
	global_store_dwordx2 v2, v[22:23], s[26:27] offset:1536
	v_mul_f32_e32 v12, v128, v10
	v_mul_f32_e32 v13, v129, v10
	v_mul_f32_e32 v14, v130, v10
	v_mul_f32_e32 v15, v131, v10
	v_mul_f32_e32 v12, v12, v96
	v_mul_f32_e32 v13, v13, v97
	v_mul_f32_e32 v14, v14, v98
	v_mul_f32_e32 v15, v15, v99
	s_waitcnt vmcnt(6)
	v_add_f32_e32 v16, 1.0, v216
	v_add_f32_e32 v17, 1.0, v217
	v_add_f32_e32 v18, 1.0, v218
	v_add_f32_e32 v19, 1.0, v219
	v_fma_f32 v12, v12, v16, v184
	v_fma_f32 v13, v13, v17, v185
	v_fma_f32 v14, v14, v18, v186
	v_fma_f32 v15, v15, v19, v187
	v_cvt_pk_bf16_f32 v20, v12, v13
	v_cvt_pk_bf16_f32 v21, v14, v15
	global_store_dwordx2 v2, v[20:21], s[26:27] offset:2048
	v_mul_f32_e32 v12, v132, v10
	v_mul_f32_e32 v13, v133, v10
	v_mul_f32_e32 v14, v134, v10
	v_mul_f32_e32 v15, v135, v10
	v_mul_f32_e32 v12, v12, v100
	v_mul_f32_e32 v13, v13, v101
	v_mul_f32_e32 v14, v14, v102
	v_mul_f32_e32 v15, v15, v103
	s_waitcnt vmcnt(4)
	v_add_f32_e32 v16, 1.0, v220
	v_add_f32_e32 v17, 1.0, v221
	v_add_f32_e32 v18, 1.0, v222
	v_add_f32_e32 v19, 1.0, v223
	v_fma_f32 v12, v12, v16, v188
	v_fma_f32 v13, v13, v17, v189
	v_fma_f32 v14, v14, v18, v190
	v_fma_f32 v15, v15, v19, v191
	v_cvt_pk_bf16_f32 v22, v12, v13
	v_cvt_pk_bf16_f32 v23, v14, v15
	global_store_dwordx2 v2, v[22:23], s[26:27] offset:2560
	v_mul_f32_e32 v12, v136, v10
	v_mul_f32_e32 v13, v137, v10
	v_mul_f32_e32 v14, v138, v10
	v_mul_f32_e32 v15, v139, v10
	v_mul_f32_e32 v12, v12, v104
	v_mul_f32_e32 v13, v13, v105
	v_mul_f32_e32 v14, v14, v106
	v_mul_f32_e32 v15, v15, v107
	s_waitcnt vmcnt(2)
	v_add_f32_e32 v16, 1.0, v224
	v_add_f32_e32 v17, 1.0, v225
	v_add_f32_e32 v18, 1.0, v226
	v_add_f32_e32 v19, 1.0, v227
	v_fma_f32 v12, v12, v16, v192
	v_fma_f32 v13, v13, v17, v193
	v_fma_f32 v14, v14, v18, v194
	v_fma_f32 v15, v15, v19, v195
	v_cvt_pk_bf16_f32 v20, v12, v13
	v_cvt_pk_bf16_f32 v21, v14, v15
	global_store_dwordx2 v2, v[20:21], s[26:27] offset:3072
	v_mul_f32_e32 v12, v140, v10
	v_mul_f32_e32 v13, v141, v10
	v_mul_f32_e32 v14, v142, v10
	v_mul_f32_e32 v15, v143, v10
	v_mul_f32_e32 v12, v12, v108
	v_mul_f32_e32 v13, v13, v109
	v_mul_f32_e32 v14, v14, v110
	v_mul_f32_e32 v15, v15, v111
	s_waitcnt vmcnt(0)
; DI void norm0_phase(const P& p, unsigned char* smem) {
;     ...
;         for (int i = 0; i < 8; ++i) {
;             const int j = i * 256 + lane * 4;
;             const f32x4 gw = *(const f32x4*)(p.norm_pre + j), sh = *(const f32x4*)(md + j), scl = *(const f32x4*)(md + 2048 + j);
;             float o[4];
; #pragma unroll
;             for (int e = 0; e < 4; ++e) o[e] = v[i][e] * rstd * gw[e] * (1.f + scl[e]) + sh[e];
;             u32x2 w; w.x = pk2(o[0], o[1]); w.y = pk2(o[2], o[3]);
;             *(u32x2*)(nb + (size_t)row * DM + j) = w;
	v_add_f32_e32 v16, 1.0, v228
	v_add_f32_e32 v17, 1.0, v229
	v_add_f32_e32 v18, 1.0, v230
	v_add_f32_e32 v19, 1.0, v231
	v_fma_f32 v12, v12, v16, v196
	v_fma_f32 v13, v13, v17, v197
	v_fma_f32 v14, v14, v18, v198
	v_fma_f32 v15, v15, v19, v199
	v_cvt_pk_bf16_f32 v22, v12, v13
	v_cvt_pk_bf16_f32 v23, v14, v15
	global_store_dwordx2 v2, v[22:23], s[26:27] offset:3584
	v_mul_f32_e32 v12, v144, v11
	v_mul_f32_e32 v13, v145, v11
	v_mul_f32_e32 v14, v146, v11
	v_mul_f32_e32 v15, v147, v11
	v_mul_f32_e32 v12, v12, v80
	v_mul_f32_e32 v13, v13, v81
	v_mul_f32_e32 v14, v14, v82
	v_mul_f32_e32 v15, v15, v83
	v_add_f32_e32 v16, 1.0, v200
	v_add_f32_e32 v17, 1.0, v201
	v_add_f32_e32 v18, 1.0, v202
	v_add_f32_e32 v19, 1.0, v203
	v_fma_f32 v12, v12, v16, v168
	v_fma_f32 v13, v13, v17, v169
	v_fma_f32 v14, v14, v18, v170
	v_fma_f32 v15, v15, v19, v171
	v_cvt_pk_bf16_f32 v20, v12, v13
	v_cvt_pk_bf16_f32 v21, v14, v15
	global_store_dwordx2 v3, v[20:21], s[26:27] offset:0
	v_mul_f32_e32 v12, v148, v11
	v_mul_f32_e32 v13, v149, v11
	v_mul_f32_e32 v14, v150, v11
	v_mul_f32_e32 v15, v151, v11
	v_mul_f32_e32 v12, v12, v84
	v_mul_f32_e32 v13, v13, v85
	v_mul_f32_e32 v14, v14, v86
	v_mul_f32_e32 v15, v15, v87
	v_add_f32_e32 v16, 1.0, v204
	v_add_f32_e32 v17, 1.0, v205
	v_add_f32_e32 v18, 1.0, v206
	v_add_f32_e32 v19, 1.0, v207
	v_fma_f32 v12, v12, v16, v172
	v_fma_f32 v13, v13, v17, v173
	v_fma_f32 v14, v14, v18, v174
	v_fma_f32 v15, v15, v19, v175
	v_cvt_pk_bf16_f32 v22, v12, v13
	v_cvt_pk_bf16_f32 v23, v14, v15
	global_store_dwordx2 v3, v[22:23], s[26:27] offset:512
	v_mul_f32_e32 v12, v152, v11
	v_mul_f32_e32 v13, v153, v11
	v_mul_f32_e32 v14, v154, v11
	v_mul_f32_e32 v15, v155, v11
	v_mul_f32_e32 v12, v12, v88
	v_mul_f32_e32 v13, v13, v89
	v_mul_f32_e32 v14, v14, v90
	v_mul_f32_e32 v15, v15, v91
	v_add_f32_e32 v16, 1.0, v208
	v_add_f32_e32 v17, 1.0, v209
	v_add_f32_e32 v18, 1.0, v210
	v_add_f32_e32 v19, 1.0, v211
	v_fma_f32 v12, v12, v16, v176
	v_fma_f32 v13, v13, v17, v177
	v_fma_f32 v14, v14, v18, v178
	v_fma_f32 v15, v15, v19, v179
	v_cvt_pk_bf16_f32 v20, v12, v13
	v_cvt_pk_bf16_f32 v21, v14, v15
	global_store_dwordx2 v3, v[20:21], s[26:27] offset:1024
	v_mul_f32_e32 v12, v156, v11
	v_mul_f32_e32 v13, v157, v11
	v_mul_f32_e32 v14, v158, v11
	v_mul_f32_e32 v15, v159, v11
	v_mul_f32_e32 v12, v12, v92
	v_mul_f32_e32 v13, v13, v93
	v_mul_f32_e32 v14, v14, v94
	v_mul_f32_e32 v15, v15, v95
	v_add_f32_e32 v16, 1.0, v212
	v_add_f32_e32 v17, 1.0, v213
	v_add_f32_e32 v18, 1.0, v214
	v_add_f32_e32 v19, 1.0, v215
	v_fma_f32 v12, v12, v16, v180
	v_fma_f32 v13, v13, v17, v181
	v_fma_f32 v14, v14, v18, v182
	v_fma_f32 v15, v15, v19, v183
	v_cvt_pk_bf16_f32 v22, v12, v13
	v_cvt_pk_bf16_f32 v23, v14, v15
	global_store_dwordx2 v3, v[22:23], s[26:27] offset:1536
	v_mul_f32_e32 v12, v160, v11
	v_mul_f32_e32 v13, v161, v11
	v_mul_f32_e32 v14, v162, v11
	v_mul_f32_e32 v15, v163, v11
	v_mul_f32_e32 v12, v12, v96
	v_mul_f32_e32 v13, v13, v97
	v_mul_f32_e32 v14, v14, v98
	v_mul_f32_e32 v15, v15, v99
	v_add_f32_e32 v16, 1.0, v216
	v_add_f32_e32 v17, 1.0, v217
	v_add_f32_e32 v18, 1.0, v218
	v_add_f32_e32 v19, 1.0, v219
	v_fma_f32 v12, v12, v16, v184
	v_fma_f32 v13, v13, v17, v185
	v_fma_f32 v14, v14, v18, v186
	v_fma_f32 v15, v15, v19, v187
	v_cvt_pk_bf16_f32 v20, v12, v13
	v_cvt_pk_bf16_f32 v21, v14, v15
	global_store_dwordx2 v3, v[20:21], s[26:27] offset:2048
	v_mul_f32_e32 v12, v232, v11
	v_mul_f32_e32 v13, v233, v11
	v_mul_f32_e32 v14, v234, v11
	v_mul_f32_e32 v15, v235, v11
	v_mul_f32_e32 v12, v12, v100
	v_mul_f32_e32 v13, v13, v101
	v_mul_f32_e32 v14, v14, v102
	v_mul_f32_e32 v15, v15, v103
	v_add_f32_e32 v16, 1.0, v220
	v_add_f32_e32 v17, 1.0, v221
	v_add_f32_e32 v18, 1.0, v222
	v_add_f32_e32 v19, 1.0, v223
	v_fma_f32 v12, v12, v16, v188
	v_fma_f32 v13, v13, v17, v189
	v_fma_f32 v14, v14, v18, v190
	v_fma_f32 v15, v15, v19, v191
	v_cvt_pk_bf16_f32 v22, v12, v13
	v_cvt_pk_bf16_f32 v23, v14, v15
	global_store_dwordx2 v3, v[22:23], s[26:27] offset:2560
	v_mul_f32_e32 v12, v236, v11
	v_mul_f32_e32 v13, v237, v11
	v_mul_f32_e32 v14, v238, v11
	v_mul_f32_e32 v15, v239, v11
	v_mul_f32_e32 v12, v12, v104
	v_mul_f32_e32 v13, v13, v105
	v_mul_f32_e32 v14, v14, v106
	v_mul_f32_e32 v15, v15, v107
	v_add_f32_e32 v16, 1.0, v224
	v_add_f32_e32 v17, 1.0, v225
	v_add_f32_e32 v18, 1.0, v226
	v_add_f32_e32 v19, 1.0, v227
	v_fma_f32 v12, v12, v16, v192
	v_fma_f32 v13, v13, v17, v193
	v_fma_f32 v14, v14, v18, v194
	v_fma_f32 v15, v15, v19, v195
	v_cvt_pk_bf16_f32 v20, v12, v13
	v_cvt_pk_bf16_f32 v21, v14, v15
	global_store_dwordx2 v3, v[20:21], s[26:27] offset:3072
	v_mul_f32_e32 v12, v240, v11
	v_mul_f32_e32 v13, v241, v11
	v_mul_f32_e32 v14, v242, v11
	v_mul_f32_e32 v15, v243, v11
	v_mul_f32_e32 v12, v12, v108
	v_mul_f32_e32 v13, v13, v109
	v_mul_f32_e32 v14, v14, v110
	v_mul_f32_e32 v15, v15, v111
	v_add_f32_e32 v16, 1.0, v228
	v_add_f32_e32 v17, 1.0, v229
	v_add_f32_e32 v18, 1.0, v230
	v_add_f32_e32 v19, 1.0, v231
	v_fma_f32 v12, v12, v16, v196
	v_fma_f32 v13, v13, v17, v197
	v_fma_f32 v14, v14, v18, v198
	v_fma_f32 v15, v15, v19, v199
	v_cvt_pk_bf16_f32 v22, v12, v13
	v_cvt_pk_bf16_f32 v23, v14, v15
	global_store_dwordx2 v3, v[22:23], s[26:27] offset:3584

; DI float lo16(unsigned u) { return __uint_as_float(u << 16); }
; DI float hi16(unsigned u) { return __uint_as_float(u & 0xFFFF0000u); }
; DI float siluf(float x) { return x * __builtin_amdgcn_rcpf(1.f + __expf(-x)); }
; DI void swa_item(const P& p, int l, int item, unsigned char* smem) {
;     ...
;     lsum += __shfl_xor(lsum, 16); lsum += __shfl_xor(lsum, 32);
;     const float inv = __builtin_amdgcn_rcpf(lsum);
; #pragma unroll
;     for (int nt = 0; nt < 8; ++nt) {
;         const int dvb = 16 * nt + 4 * g;
;         const u32x2 gw = *(const u32x2*)(S + qrow * NP + C_SWA_G + 128 * hq + dvb);
;         const float g0 = lo16(gw.x), g1 = hi16(gw.x), g2 = lo16(gw.y), g3 = hi16(gw.y);
;         u32x2 o; o.x = pk2(ot[nt][0] * inv * siluf(g0), ot[nt][1] * inv * siluf(g1)); o.y = pk2(ot[nt][2] * inv * siluf(g2), ot[nt][3] * inv * siluf(g3));
;         *(u32x2*)(Y + qrow * DM + 1536 + 128 * hq + dvb) = o;
;     }
.LBB0_390:
	v_cmp_lt_i32_e32 vcc, v107, v109
	s_waitcnt vmcnt(2)
	v_lshlrev_b64 v[34:35], 12, v[96:97]
	v_lshlrev_b64 v[30:31], 1, v[100:101]
	v_cndmask_b32_e32 v28, v105, v107, vcc
	v_lshl_add_u64 v[34:35], s[38:39], 0, v[34:35]
	v_mov_b32_e32 v107, v133
	v_lshl_add_u64 v[32:33], v[98:99], 0, v[30:31]
	v_lshl_add_u64 v[30:31], v[34:35], 0, v[30:31]
	v_lshlrev_b64 v[34:35], 1, v[106:107]
	s_waitcnt vmcnt(1)
	v_lshl_add_u64 v[36:37], v[32:33], 0, v[34:35]
	s_mov_b64 s[0:1], 0x3400
	v_cmp_lt_i32_e32 vcc, v111, v109
	v_lshl_add_u64 v[32:33], v[36:37], 0, s[0:1]
	s_movk_i32 s0, 0x3000
	v_cndmask_b32_e32 v29, v105, v111, vcc
	v_add_co_u32_e32 v36, vcc, s0, v36
	v_lshlrev_b32_e32 v28, 2, v28
	s_nop 0
	v_addc_co_u32_e32 v37, vcc, 0, v37, vcc
	global_load_dwordx2 v[36:37], v[36:37], off offset:1024
	global_load_dwordx2 v[62:63], v[32:33], off offset:32
	global_load_dwordx2 v[64:65], v[32:33], off offset:64
	global_load_dwordx2 v[66:67], v[32:33], off offset:96
	global_load_dwordx2 v[68:69], v[32:33], off offset:128
	global_load_dwordx2 v[70:71], v[32:33], off offset:160
	global_load_dwordx2 v[72:73], v[32:33], off offset:192
	global_load_dwordx2 v[74:75], v[32:33], off offset:224
	ds_bpermute_b32 v28, v28, v119
	v_lshlrev_b32_e32 v29, 2, v29
	v_lshl_add_u64 v[34:35], v[30:31], 0, v[34:35]
	s_mov_b64 s[0:1], 0xea3cc00
	v_lshl_add_u64 v[30:31], v[34:35], 0, s[0:1]
	s_waitcnt lgkmcnt(0)
	v_add_f32_e32 v28, v119, v28
	ds_bpermute_b32 v29, v29, v28
	s_mov_b32 s0, 0xea3c000
	v_add_co_u32_e32 v34, vcc, s0, v34
	v_readlane_b32 s0, v254, 15
	s_waitcnt lgkmcnt(0)
	v_add_f32_e32 v28, v28, v29
	v_rcp_f32_e32 v28, v28
	v_addc_co_u32_e32 v35, vcc, 0, v35, vcc
	s_add_i32 s21, s0, s21
	s_cmp_ge_i32 s21, s13
	s_waitcnt vmcnt(7)
	v_lshlrev_b32_e32 v38, 16, v36
	v_mul_f32_e32 v29, 0xbfb8aa3b, v38
	v_exp_f32_e32 v29, v29
	v_and_b32_e32 v39, 0xffff0000, v36
	v_add_f32_e32 v29, 1.0, v29
	v_rcp_f32_e32 v40, v29
	v_pk_mul_f32 v[42:43], v[48:49], v[28:29] op_sel_hi:[1,0]
	v_mul_f32_e32 v29, 0xbfb8aa3b, v39
	v_exp_f32_e32 v29, v29
	s_nop 0
	v_add_f32_e32 v29, 1.0, v29
	v_rcp_f32_e32 v41, v29
	s_nop 0
	v_pk_mul_f32 v[38:39], v[40:41], v[38:39]
	s_nop 0
	v_pk_mul_f32 v[38:39], v[42:43], v[38:39]
	s_nop 0
	v_cvt_pk_bf16_f32 v36, v38, v39
	v_lshlrev_b32_e32 v38, 16, v37
	v_mul_f32_e32 v29, 0xbfb8aa3b, v38
	v_exp_f32_e32 v29, v29
	v_and_b32_e32 v39, 0xffff0000, v37
	v_add_f32_e32 v29, 1.0, v29
	v_rcp_f32_e32 v40, v29
	v_pk_mul_f32 v[42:43], v[50:51], v[28:29] op_sel_hi:[1,0]
	v_mul_f32_e32 v29, 0xbfb8aa3b, v39
	v_exp_f32_e32 v29, v29
	s_nop 0
	v_add_f32_e32 v29, 1.0, v29
	v_rcp_f32_e32 v41, v29
	s_nop 0
	v_pk_mul_f32 v[38:39], v[40:41], v[38:39]
	s_nop 0
	v_pk_mul_f32 v[38:39], v[42:43], v[38:39]
	s_nop 0
	v_cvt_pk_bf16_f32 v37, v38, v39
	global_store_dwordx2 v[34:35], v[36:37], off offset:3072
	s_waitcnt vmcnt(6)
	v_mov_b32_e32 v34, v62
	v_mov_b32_e32 v35, v63
	v_lshlrev_b32_e32 v36, 16, v34
	v_mul_f32_e32 v29, 0xbfb8aa3b, v36
	v_exp_f32_e32 v29, v29
	v_and_b32_e32 v37, 0xffff0000, v34
	v_lshlrev_b32_e32 v34, 16, v35
	v_and_b32_e32 v35, 0xffff0000, v35
	v_add_f32_e32 v29, 1.0, v29
	v_rcp_f32_e32 v38, v29
	v_pk_mul_f32 v[24:25], v[24:25], v[28:29] op_sel_hi:[1,0]
	v_mul_f32_e32 v29, 0xbfb8aa3b, v37
	v_exp_f32_e32 v29, v29
	s_nop 0
	v_add_f32_e32 v29, 1.0, v29
	v_rcp_f32_e32 v39, v29
	v_pk_mul_f32 v[26:27], v[26:27], v[28:29] op_sel_hi:[1,0]
	v_pk_mul_f32 v[20:21], v[20:21], v[28:29] op_sel_hi:[1,0]
	v_pk_mul_f32 v[22:23], v[22:23], v[28:29] op_sel_hi:[1,0]
	v_pk_mul_f32 v[36:37], v[38:39], v[36:37]
	v_pk_mul_f32 v[16:17], v[16:17], v[28:29] op_sel_hi:[1,0]
	v_pk_mul_f32 v[24:25], v[24:25], v[36:37]
	v_pk_mul_f32 v[18:19], v[18:19], v[28:29] op_sel_hi:[1,0]
	v_cvt_pk_bf16_f32 v24, v24, v25
	v_mul_f32_e32 v25, 0xbfb8aa3b, v34
	v_exp_f32_e32 v25, v25
	v_pk_mul_f32 v[12:13], v[12:13], v[28:29] op_sel_hi:[1,0]
	v_pk_mul_f32 v[14:15], v[14:15], v[28:29] op_sel_hi:[1,0]
	v_pk_mul_f32 v[8:9], v[8:9], v[28:29] op_sel_hi:[1,0]
	v_add_f32_e32 v25, 1.0, v25
	v_rcp_f32_e32 v36, v25
	v_mul_f32_e32 v25, 0xbfb8aa3b, v35
	v_exp_f32_e32 v25, v25
	v_pk_mul_f32 v[10:11], v[10:11], v[28:29] op_sel_hi:[1,0]
	v_pk_mul_f32 v[4:5], v[4:5], v[28:29] op_sel_hi:[1,0]
	v_pk_mul_f32 v[6:7], v[6:7], v[28:29] op_sel_hi:[1,0]
	v_add_f32_e32 v25, 1.0, v25
	v_rcp_f32_e32 v37, v25
	v_pk_mul_f32 v[0:1], v[0:1], v[28:29] op_sel_hi:[1,0]
	v_pk_mul_f32 v[2:3], v[2:3], v[28:29] op_sel_hi:[1,0]
	v_pk_mul_f32 v[34:35], v[36:37], v[34:35]
	s_nop 0
	v_pk_mul_f32 v[26:27], v[26:27], v[34:35]
	s_nop 0
	v_cvt_pk_bf16_f32 v25, v26, v27
	global_store_dwordx2 v[30:31], v[24:25], off offset:32
	s_waitcnt vmcnt(5)
	v_mov_b32_e32 v24, v64
	v_mov_b32_e32 v25, v65
	v_lshlrev_b32_e32 v26, 16, v24
	v_and_b32_e32 v27, 0xffff0000, v24
	v_mul_f32_e32 v24, 0xbfb8aa3b, v26
	v_exp_f32_e32 v24, v24
	s_nop 0
	v_add_f32_e32 v24, 1.0, v24
	v_rcp_f32_e32 v34, v24
	v_mul_f32_e32 v24, 0xbfb8aa3b, v27
	v_exp_f32_e32 v24, v24
	s_nop 0
	v_add_f32_e32 v24, 1.0, v24
	v_rcp_f32_e32 v35, v24
	v_lshlrev_b32_e32 v24, 16, v25
	v_and_b32_e32 v25, 0xffff0000, v25
	v_pk_mul_f32 v[26:27], v[34:35], v[26:27]
	s_nop 0
	v_pk_mul_f32 v[20:21], v[20:21], v[26:27]
	s_nop 0
	v_cvt_pk_bf16_f32 v20, v20, v21
	v_mul_f32_e32 v21, 0xbfb8aa3b, v24
	v_exp_f32_e32 v21, v21
	s_nop 0
	v_add_f32_e32 v21, 1.0, v21
	v_rcp_f32_e32 v26, v21
	v_mul_f32_e32 v21, 0xbfb8aa3b, v25
	v_exp_f32_e32 v21, v21
	s_nop 0
	v_add_f32_e32 v21, 1.0, v21
	v_rcp_f32_e32 v27, v21
	s_nop 0
	v_pk_mul_f32 v[24:25], v[26:27], v[24:25]
	s_nop 0
	v_pk_mul_f32 v[22:23], v[22:23], v[24:25]
	s_nop 0
	v_cvt_pk_bf16_f32 v21, v22, v23
	global_store_dwordx2 v[30:31], v[20:21], off offset:64
	s_waitcnt vmcnt(4)
; DI float lo16(unsigned u) { return __uint_as_float(u << 16); }
; DI float hi16(unsigned u) { return __uint_as_float(u & 0xFFFF0000u); }
; DI float siluf(float x) { return x * __builtin_amdgcn_rcpf(1.f + __expf(-x)); }
; DI void swa_item(const P& p, int l, int item, unsigned char* smem) {
;     ...
;     lsum += __shfl_xor(lsum, 16); lsum += __shfl_xor(lsum, 32);
;     const float inv = __builtin_amdgcn_rcpf(lsum);
; #pragma unroll
;     for (int nt = 0; nt < 8; ++nt) {
;         const int dvb = 16 * nt + 4 * g;
;         const u32x2 gw = *(const u32x2*)(S + qrow * NP + C_SWA_G + 128 * hq + dvb);
;         const float g0 = lo16(gw.x), g1 = hi16(gw.x), g2 = lo16(gw.y), g3 = hi16(gw.y);
;         u32x2 o; o.x = pk2(ot[nt][0] * inv * siluf(g0), ot[nt][1] * inv * siluf(g1)); o.y = pk2(ot[nt][2] * inv * siluf(g2), ot[nt][3] * inv * siluf(g3));
;         *(u32x2*)(Y + qrow * DM + 1536 + 128 * hq + dvb) = o;
;     }
	v_mov_b32_e32 v20, v66
	v_mov_b32_e32 v21, v67
	v_lshlrev_b32_e32 v22, 16, v20
	v_and_b32_e32 v23, 0xffff0000, v20
	v_mul_f32_e32 v20, 0xbfb8aa3b, v22
	v_exp_f32_e32 v20, v20
	s_nop 0
	v_add_f32_e32 v20, 1.0, v20
	v_rcp_f32_e32 v24, v20
	v_mul_f32_e32 v20, 0xbfb8aa3b, v23
	v_exp_f32_e32 v20, v20
	s_nop 0
	v_add_f32_e32 v20, 1.0, v20
	v_rcp_f32_e32 v25, v20
	v_lshlrev_b32_e32 v20, 16, v21
	v_and_b32_e32 v21, 0xffff0000, v21
	v_pk_mul_f32 v[22:23], v[24:25], v[22:23]
	s_nop 0
	v_pk_mul_f32 v[16:17], v[16:17], v[22:23]
	s_nop 0
	v_cvt_pk_bf16_f32 v16, v16, v17
	v_mul_f32_e32 v17, 0xbfb8aa3b, v20
	v_exp_f32_e32 v17, v17
	s_nop 0
	v_add_f32_e32 v17, 1.0, v17
	v_rcp_f32_e32 v22, v17
	v_mul_f32_e32 v17, 0xbfb8aa3b, v21
	v_exp_f32_e32 v17, v17
	s_nop 0
	v_add_f32_e32 v17, 1.0, v17
	v_rcp_f32_e32 v23, v17
	s_nop 0
	v_pk_mul_f32 v[20:21], v[22:23], v[20:21]
	s_nop 0
	v_pk_mul_f32 v[18:19], v[18:19], v[20:21]
	s_nop 0
	v_cvt_pk_bf16_f32 v17, v18, v19
	global_store_dwordx2 v[30:31], v[16:17], off offset:96
	s_waitcnt vmcnt(3)
	v_mov_b32_e32 v16, v68
	v_mov_b32_e32 v17, v69
	v_lshlrev_b32_e32 v18, 16, v16
	v_and_b32_e32 v19, 0xffff0000, v16
	v_mul_f32_e32 v16, 0xbfb8aa3b, v18
	v_exp_f32_e32 v16, v16
	s_nop 0
	v_add_f32_e32 v16, 1.0, v16
	v_rcp_f32_e32 v20, v16
	v_mul_f32_e32 v16, 0xbfb8aa3b, v19
	v_exp_f32_e32 v16, v16
	s_nop 0
	v_add_f32_e32 v16, 1.0, v16
	v_rcp_f32_e32 v21, v16
	v_lshlrev_b32_e32 v16, 16, v17
	v_and_b32_e32 v17, 0xffff0000, v17
	v_pk_mul_f32 v[18:19], v[20:21], v[18:19]
	s_nop 0
	v_pk_mul_f32 v[12:13], v[12:13], v[18:19]
	s_nop 0
	v_cvt_pk_bf16_f32 v12, v12, v13
	v_mul_f32_e32 v13, 0xbfb8aa3b, v16
	v_exp_f32_e32 v13, v13
	s_nop 0
	v_add_f32_e32 v13, 1.0, v13
	v_rcp_f32_e32 v18, v13
	v_mul_f32_e32 v13, 0xbfb8aa3b, v17
	v_exp_f32_e32 v13, v13
	s_nop 0
	v_add_f32_e32 v13, 1.0, v13
	v_rcp_f32_e32 v19, v13
	s_nop 0
	v_pk_mul_f32 v[16:17], v[18:19], v[16:17]
	s_nop 0
	v_pk_mul_f32 v[14:15], v[14:15], v[16:17]
	s_nop 0
	v_cvt_pk_bf16_f32 v13, v14, v15
	global_store_dwordx2 v[30:31], v[12:13], off offset:128
	s_waitcnt vmcnt(2)
	v_mov_b32_e32 v12, v70
	v_mov_b32_e32 v13, v71
	v_lshlrev_b32_e32 v14, 16, v12
	v_and_b32_e32 v15, 0xffff0000, v12
	v_mul_f32_e32 v12, 0xbfb8aa3b, v14
	v_exp_f32_e32 v12, v12
	s_nop 0
	v_add_f32_e32 v12, 1.0, v12
	v_rcp_f32_e32 v16, v12
	v_mul_f32_e32 v12, 0xbfb8aa3b, v15
	v_exp_f32_e32 v12, v12
	s_nop 0
	v_add_f32_e32 v12, 1.0, v12
	v_rcp_f32_e32 v17, v12
	v_lshlrev_b32_e32 v12, 16, v13
	v_and_b32_e32 v13, 0xffff0000, v13
	v_pk_mul_f32 v[14:15], v[16:17], v[14:15]
	s_nop 0
	v_pk_mul_f32 v[8:9], v[8:9], v[14:15]
	s_nop 0
	v_cvt_pk_bf16_f32 v8, v8, v9
	v_mul_f32_e32 v9, 0xbfb8aa3b, v12
	v_exp_f32_e32 v9, v9
	s_nop 0
	v_add_f32_e32 v9, 1.0, v9
	v_rcp_f32_e32 v14, v9
	v_mul_f32_e32 v9, 0xbfb8aa3b, v13
	v_exp_f32_e32 v9, v9
	s_nop 0
	v_add_f32_e32 v9, 1.0, v9
	v_rcp_f32_e32 v15, v9
	s_nop 0
	v_pk_mul_f32 v[12:13], v[14:15], v[12:13]
	s_nop 0
	v_pk_mul_f32 v[10:11], v[10:11], v[12:13]
	s_nop 0
	v_cvt_pk_bf16_f32 v9, v10, v11
	global_store_dwordx2 v[30:31], v[8:9], off offset:160
	s_waitcnt vmcnt(1)
	v_mov_b32_e32 v8, v72
	v_mov_b32_e32 v9, v73
	v_lshlrev_b32_e32 v10, 16, v8
	v_and_b32_e32 v11, 0xffff0000, v8
	v_mul_f32_e32 v8, 0xbfb8aa3b, v10
	v_exp_f32_e32 v8, v8
	s_nop 0
	v_add_f32_e32 v8, 1.0, v8
	v_rcp_f32_e32 v12, v8
	v_mul_f32_e32 v8, 0xbfb8aa3b, v11
	v_exp_f32_e32 v8, v8
	s_nop 0
	v_add_f32_e32 v8, 1.0, v8
	v_rcp_f32_e32 v13, v8
	v_lshlrev_b32_e32 v8, 16, v9
	v_and_b32_e32 v9, 0xffff0000, v9
	v_pk_mul_f32 v[10:11], v[12:13], v[10:11]
	s_nop 0
	v_pk_mul_f32 v[4:5], v[4:5], v[10:11]
	s_nop 0
	v_cvt_pk_bf16_f32 v4, v4, v5
	v_mul_f32_e32 v5, 0xbfb8aa3b, v8
	v_exp_f32_e32 v5, v5
	s_nop 0
	v_add_f32_e32 v5, 1.0, v5
	v_rcp_f32_e32 v10, v5
	v_mul_f32_e32 v5, 0xbfb8aa3b, v9
	v_exp_f32_e32 v5, v5
	s_nop 0
	v_add_f32_e32 v5, 1.0, v5
	v_rcp_f32_e32 v11, v5
	s_nop 0
	v_pk_mul_f32 v[8:9], v[10:11], v[8:9]
	s_nop 0
	v_pk_mul_f32 v[6:7], v[6:7], v[8:9]
	s_nop 0
	v_cvt_pk_bf16_f32 v5, v6, v7
	global_store_dwordx2 v[30:31], v[4:5], off offset:192
	s_waitcnt vmcnt(0)
	v_mov_b32_e32 v4, v74
	v_mov_b32_e32 v5, v75
	v_lshlrev_b32_e32 v6, 16, v4
	v_and_b32_e32 v7, 0xffff0000, v4
	v_mul_f32_e32 v4, 0xbfb8aa3b, v6
	v_exp_f32_e32 v4, v4
	s_nop 0
	v_add_f32_e32 v4, 1.0, v4
	v_rcp_f32_e32 v8, v4
	v_mul_f32_e32 v4, 0xbfb8aa3b, v7
	v_exp_f32_e32 v4, v4
	s_nop 0
	v_add_f32_e32 v4, 1.0, v4
	v_rcp_f32_e32 v9, v4
	v_lshlrev_b32_e32 v4, 16, v5
	v_and_b32_e32 v5, 0xffff0000, v5
	v_pk_mul_f32 v[6:7], v[8:9], v[6:7]
	s_nop 0
	v_pk_mul_f32 v[0:1], v[0:1], v[6:7]
	s_nop 0
	v_cvt_pk_bf16_f32 v0, v0, v1
	v_mul_f32_e32 v1, 0xbfb8aa3b, v4
	v_exp_f32_e32 v1, v1
	s_nop 0
	v_add_f32_e32 v1, 1.0, v1
	v_rcp_f32_e32 v6, v1
	v_mul_f32_e32 v1, 0xbfb8aa3b, v5
	v_exp_f32_e32 v1, v1
	s_nop 0
	v_add_f32_e32 v1, 1.0, v1
	v_rcp_f32_e32 v7, v1
	s_nop 0
	v_pk_mul_f32 v[4:5], v[6:7], v[4:5]
	s_nop 0
	v_pk_mul_f32 v[2:3], v[2:3], v[4:5]
	s_nop 0
	v_cvt_pk_bf16_f32 v1, v2, v3
	global_store_dwordx2 v[30:31], v[0:1], off offset:224
	s_cbranch_scc1 .LBB0_385

; DI float lo16(unsigned u) { return __uint_as_float(u << 16); }
; DI float hi16(unsigned u) { return __uint_as_float(u & 0xFFFF0000u); }
; DI float siluf(float x) { return x * __builtin_amdgcn_rcpf(1.f + __expf(-x)); }
; DI void swa_item(const P& p, int l, int item, unsigned char* smem) {
;     ...
;     lsum += __shfl_xor(lsum, 16); lsum += __shfl_xor(lsum, 32);
;     const float inv = __builtin_amdgcn_rcpf(lsum);
; #pragma unroll
;     for (int nt = 0; nt < 8; ++nt) {
;         const int dvb = 16 * nt + 4 * g;
;         const u32x2 gw = *(const u32x2*)(S + qrow * NP + C_SWA_G + 128 * hq + dvb);
;         const float g0 = lo16(gw.x), g1 = hi16(gw.x), g2 = lo16(gw.y), g3 = hi16(gw.y);
;         u32x2 o; o.x = pk2(ot[nt][0] * inv * siluf(g0), ot[nt][1] * inv * siluf(g1)); o.y = pk2(ot[nt][2] * inv * siluf(g2), ot[nt][3] * inv * siluf(g3));
;         *(u32x2*)(Y + qrow * DM + 1536 + 128 * hq + dvb) = o;
;     }
.LBB0_432:
	v_cmp_lt_i32_e32 vcc, v105, v107
	s_waitcnt vmcnt(2)
	v_lshlrev_b64 v[34:35], 12, v[96:97]
	v_lshlrev_b64 v[30:31], 1, v[100:101]
	v_cndmask_b32_e32 v28, v59, v105, vcc
	v_cmp_lt_i32_e32 vcc, v109, v107
	v_lshl_add_u64 v[34:35], s[38:39], 0, v[34:35]
	v_mov_b32_e32 v107, v133
	v_lshl_add_u64 v[32:33], v[98:99], 0, v[30:31]
	v_lshl_add_u64 v[30:31], v[34:35], 0, v[30:31]
	v_lshlrev_b64 v[34:35], 1, v[106:107]
	s_waitcnt vmcnt(1)
	v_lshl_add_u64 v[36:37], v[32:33], 0, v[34:35]
	s_mov_b64 s[0:1], 0x3400
	v_lshl_add_u64 v[32:33], v[36:37], 0, s[0:1]
	s_movk_i32 s0, 0x3000
	v_cndmask_b32_e32 v29, v59, v109, vcc
	v_add_co_u32_e32 v36, vcc, s0, v36
	v_lshlrev_b32_e32 v28, 2, v28
	s_nop 0
	v_addc_co_u32_e32 v37, vcc, 0, v37, vcc
	global_load_dwordx2 v[36:37], v[36:37], off offset:1024
	global_load_dwordx2 v[62:63], v[32:33], off offset:32
	global_load_dwordx2 v[64:65], v[32:33], off offset:64
	global_load_dwordx2 v[66:67], v[32:33], off offset:96
	global_load_dwordx2 v[68:69], v[32:33], off offset:128
	global_load_dwordx2 v[70:71], v[32:33], off offset:160
	global_load_dwordx2 v[72:73], v[32:33], off offset:192
	global_load_dwordx2 v[74:75], v[32:33], off offset:224
	ds_bpermute_b32 v28, v28, v118
	v_lshlrev_b32_e32 v29, 2, v29
	v_lshl_add_u64 v[34:35], v[30:31], 0, v[34:35]
	s_mov_b64 s[0:1], 0xea3cc00
	v_lshl_add_u64 v[30:31], v[34:35], 0, s[0:1]
	s_waitcnt lgkmcnt(0)
	v_add_f32_e32 v28, v118, v28
	ds_bpermute_b32 v29, v29, v28
	s_mov_b32 s0, 0xea3c000
	v_add_co_u32_e32 v34, vcc, s0, v34
	s_add_i32 s51, s51, 12
	s_waitcnt lgkmcnt(0)
	v_add_f32_e32 v28, v28, v29
	v_rcp_f32_e32 v28, v28
	v_addc_co_u32_e32 v35, vcc, 0, v35, vcc
	s_cmp_ge_u32 s51, s21
	s_waitcnt vmcnt(7)
	v_lshlrev_b32_e32 v38, 16, v36
	v_mul_f32_e32 v29, 0xbfb8aa3b, v38
	v_exp_f32_e32 v29, v29
	v_and_b32_e32 v39, 0xffff0000, v36
	v_add_f32_e32 v29, 1.0, v29
	v_rcp_f32_e32 v40, v29
	v_pk_mul_f32 v[42:43], v[48:49], v[28:29] op_sel_hi:[1,0]
	v_mul_f32_e32 v29, 0xbfb8aa3b, v39
	v_exp_f32_e32 v29, v29
	s_nop 0
	v_add_f32_e32 v29, 1.0, v29
	v_rcp_f32_e32 v41, v29
	s_nop 0
	v_pk_mul_f32 v[38:39], v[40:41], v[38:39]
	s_nop 0
	v_pk_mul_f32 v[38:39], v[42:43], v[38:39]
	s_nop 0
	v_cvt_pk_bf16_f32 v36, v38, v39
	v_lshlrev_b32_e32 v38, 16, v37
	v_mul_f32_e32 v29, 0xbfb8aa3b, v38
	v_exp_f32_e32 v29, v29
	v_and_b32_e32 v39, 0xffff0000, v37
	v_add_f32_e32 v29, 1.0, v29
	v_rcp_f32_e32 v40, v29
	v_pk_mul_f32 v[42:43], v[50:51], v[28:29] op_sel_hi:[1,0]
	v_mul_f32_e32 v29, 0xbfb8aa3b, v39
	v_exp_f32_e32 v29, v29
	s_nop 0
	v_add_f32_e32 v29, 1.0, v29
	v_rcp_f32_e32 v41, v29
	s_nop 0
	v_pk_mul_f32 v[38:39], v[40:41], v[38:39]
	s_nop 0
	v_pk_mul_f32 v[38:39], v[42:43], v[38:39]
	s_nop 0
	v_cvt_pk_bf16_f32 v37, v38, v39
	global_store_dwordx2 v[34:35], v[36:37], off offset:3072
	s_waitcnt vmcnt(6)
	v_mov_b32_e32 v34, v62
	v_mov_b32_e32 v35, v63
	v_lshlrev_b32_e32 v36, 16, v34
	v_mul_f32_e32 v29, 0xbfb8aa3b, v36
	v_exp_f32_e32 v29, v29
	v_and_b32_e32 v37, 0xffff0000, v34
	v_lshlrev_b32_e32 v34, 16, v35
	v_and_b32_e32 v35, 0xffff0000, v35
	v_add_f32_e32 v29, 1.0, v29
	v_rcp_f32_e32 v38, v29
	v_pk_mul_f32 v[24:25], v[24:25], v[28:29] op_sel_hi:[1,0]
	v_mul_f32_e32 v29, 0xbfb8aa3b, v37
	v_exp_f32_e32 v29, v29
	s_nop 0
	v_add_f32_e32 v29, 1.0, v29
	v_rcp_f32_e32 v39, v29
	v_pk_mul_f32 v[26:27], v[26:27], v[28:29] op_sel_hi:[1,0]
	v_pk_mul_f32 v[20:21], v[20:21], v[28:29] op_sel_hi:[1,0]
	v_pk_mul_f32 v[22:23], v[22:23], v[28:29] op_sel_hi:[1,0]
	v_pk_mul_f32 v[36:37], v[38:39], v[36:37]
	v_pk_mul_f32 v[16:17], v[16:17], v[28:29] op_sel_hi:[1,0]
	v_pk_mul_f32 v[24:25], v[24:25], v[36:37]
	v_pk_mul_f32 v[18:19], v[18:19], v[28:29] op_sel_hi:[1,0]
	v_cvt_pk_bf16_f32 v24, v24, v25
	v_mul_f32_e32 v25, 0xbfb8aa3b, v34
	v_exp_f32_e32 v25, v25
	v_pk_mul_f32 v[12:13], v[12:13], v[28:29] op_sel_hi:[1,0]
	v_pk_mul_f32 v[14:15], v[14:15], v[28:29] op_sel_hi:[1,0]
	v_pk_mul_f32 v[8:9], v[8:9], v[28:29] op_sel_hi:[1,0]
	v_add_f32_e32 v25, 1.0, v25
	v_rcp_f32_e32 v36, v25
	v_mul_f32_e32 v25, 0xbfb8aa3b, v35
	v_exp_f32_e32 v25, v25
	v_pk_mul_f32 v[10:11], v[10:11], v[28:29] op_sel_hi:[1,0]
	v_pk_mul_f32 v[4:5], v[4:5], v[28:29] op_sel_hi:[1,0]
	v_pk_mul_f32 v[6:7], v[6:7], v[28:29] op_sel_hi:[1,0]
	v_add_f32_e32 v25, 1.0, v25
	v_rcp_f32_e32 v37, v25
	v_pk_mul_f32 v[0:1], v[0:1], v[28:29] op_sel_hi:[1,0]
	v_pk_mul_f32 v[2:3], v[2:3], v[28:29] op_sel_hi:[1,0]
	v_pk_mul_f32 v[34:35], v[36:37], v[34:35]
	s_nop 0
	v_pk_mul_f32 v[26:27], v[26:27], v[34:35]
	s_nop 0
	v_cvt_pk_bf16_f32 v25, v26, v27
	global_store_dwordx2 v[30:31], v[24:25], off offset:32
	s_waitcnt vmcnt(5)
	v_mov_b32_e32 v24, v64
	v_mov_b32_e32 v25, v65
	v_lshlrev_b32_e32 v26, 16, v24
	v_and_b32_e32 v27, 0xffff0000, v24
	v_mul_f32_e32 v24, 0xbfb8aa3b, v26
	v_exp_f32_e32 v24, v24
	s_nop 0
	v_add_f32_e32 v24, 1.0, v24
	v_rcp_f32_e32 v34, v24
	v_mul_f32_e32 v24, 0xbfb8aa3b, v27
	v_exp_f32_e32 v24, v24
	s_nop 0
	v_add_f32_e32 v24, 1.0, v24
	v_rcp_f32_e32 v35, v24
	v_lshlrev_b32_e32 v24, 16, v25
	v_and_b32_e32 v25, 0xffff0000, v25
	v_pk_mul_f32 v[26:27], v[34:35], v[26:27]
	s_nop 0
	v_pk_mul_f32 v[20:21], v[20:21], v[26:27]
	s_nop 0
	v_cvt_pk_bf16_f32 v20, v20, v21
	v_mul_f32_e32 v21, 0xbfb8aa3b, v24
	v_exp_f32_e32 v21, v21
	s_nop 0
	v_add_f32_e32 v21, 1.0, v21
	v_rcp_f32_e32 v26, v21
	v_mul_f32_e32 v21, 0xbfb8aa3b, v25
	v_exp_f32_e32 v21, v21
	s_nop 0
	v_add_f32_e32 v21, 1.0, v21
	v_rcp_f32_e32 v27, v21
	s_nop 0
	v_pk_mul_f32 v[24:25], v[26:27], v[24:25]
	s_nop 0
	v_pk_mul_f32 v[22:23], v[22:23], v[24:25]
	s_nop 0
	v_cvt_pk_bf16_f32 v21, v22, v23
	global_store_dwordx2 v[30:31], v[20:21], off offset:64
	s_waitcnt vmcnt(4)
; DI float lo16(unsigned u) { return __uint_as_float(u << 16); }
; DI float hi16(unsigned u) { return __uint_as_float(u & 0xFFFF0000u); }
; DI float siluf(float x) { return x * __builtin_amdgcn_rcpf(1.f + __expf(-x)); }
; DI void swa_item(const P& p, int l, int item, unsigned char* smem) {
;     ...
;     lsum += __shfl_xor(lsum, 16); lsum += __shfl_xor(lsum, 32);
;     const float inv = __builtin_amdgcn_rcpf(lsum);
; #pragma unroll
;     for (int nt = 0; nt < 8; ++nt) {
;         const int dvb = 16 * nt + 4 * g;
;         const u32x2 gw = *(const u32x2*)(S + qrow * NP + C_SWA_G + 128 * hq + dvb);
;         const float g0 = lo16(gw.x), g1 = hi16(gw.x), g2 = lo16(gw.y), g3 = hi16(gw.y);
;         u32x2 o; o.x = pk2(ot[nt][0] * inv * siluf(g0), ot[nt][1] * inv * siluf(g1)); o.y = pk2(ot[nt][2] * inv * siluf(g2), ot[nt][3] * inv * siluf(g3));
;         *(u32x2*)(Y + qrow * DM + 1536 + 128 * hq + dvb) = o;
;     }
	v_mov_b32_e32 v20, v66
	v_mov_b32_e32 v21, v67
	v_lshlrev_b32_e32 v22, 16, v20
	v_and_b32_e32 v23, 0xffff0000, v20
	v_mul_f32_e32 v20, 0xbfb8aa3b, v22
	v_exp_f32_e32 v20, v20
	s_nop 0
	v_add_f32_e32 v20, 1.0, v20
	v_rcp_f32_e32 v24, v20
	v_mul_f32_e32 v20, 0xbfb8aa3b, v23
	v_exp_f32_e32 v20, v20
	s_nop 0
	v_add_f32_e32 v20, 1.0, v20
	v_rcp_f32_e32 v25, v20
	v_lshlrev_b32_e32 v20, 16, v21
	v_and_b32_e32 v21, 0xffff0000, v21
	v_pk_mul_f32 v[22:23], v[24:25], v[22:23]
	s_nop 0
	v_pk_mul_f32 v[16:17], v[16:17], v[22:23]
	s_nop 0
	v_cvt_pk_bf16_f32 v16, v16, v17
	v_mul_f32_e32 v17, 0xbfb8aa3b, v20
	v_exp_f32_e32 v17, v17
	s_nop 0
	v_add_f32_e32 v17, 1.0, v17
	v_rcp_f32_e32 v22, v17
	v_mul_f32_e32 v17, 0xbfb8aa3b, v21
	v_exp_f32_e32 v17, v17
	s_nop 0
	v_add_f32_e32 v17, 1.0, v17
	v_rcp_f32_e32 v23, v17
	s_nop 0
	v_pk_mul_f32 v[20:21], v[22:23], v[20:21]
	s_nop 0
	v_pk_mul_f32 v[18:19], v[18:19], v[20:21]
	s_nop 0
	v_cvt_pk_bf16_f32 v17, v18, v19
	global_store_dwordx2 v[30:31], v[16:17], off offset:96
	s_waitcnt vmcnt(3)
	v_mov_b32_e32 v16, v68
	v_mov_b32_e32 v17, v69
	v_lshlrev_b32_e32 v18, 16, v16
	v_and_b32_e32 v19, 0xffff0000, v16
	v_mul_f32_e32 v16, 0xbfb8aa3b, v18
	v_exp_f32_e32 v16, v16
	s_nop 0
	v_add_f32_e32 v16, 1.0, v16
	v_rcp_f32_e32 v20, v16
	v_mul_f32_e32 v16, 0xbfb8aa3b, v19
	v_exp_f32_e32 v16, v16
	s_nop 0
	v_add_f32_e32 v16, 1.0, v16
	v_rcp_f32_e32 v21, v16
	v_lshlrev_b32_e32 v16, 16, v17
	v_and_b32_e32 v17, 0xffff0000, v17
	v_pk_mul_f32 v[18:19], v[20:21], v[18:19]
	s_nop 0
	v_pk_mul_f32 v[12:13], v[12:13], v[18:19]
	s_nop 0
	v_cvt_pk_bf16_f32 v12, v12, v13
	v_mul_f32_e32 v13, 0xbfb8aa3b, v16
	v_exp_f32_e32 v13, v13
	s_nop 0
	v_add_f32_e32 v13, 1.0, v13
	v_rcp_f32_e32 v18, v13
	v_mul_f32_e32 v13, 0xbfb8aa3b, v17
	v_exp_f32_e32 v13, v13
	s_nop 0
	v_add_f32_e32 v13, 1.0, v13
	v_rcp_f32_e32 v19, v13
	s_nop 0
	v_pk_mul_f32 v[16:17], v[18:19], v[16:17]
	s_nop 0
	v_pk_mul_f32 v[14:15], v[14:15], v[16:17]
	s_nop 0
	v_cvt_pk_bf16_f32 v13, v14, v15
	global_store_dwordx2 v[30:31], v[12:13], off offset:128
	s_waitcnt vmcnt(2)
	v_mov_b32_e32 v12, v70
	v_mov_b32_e32 v13, v71
	v_lshlrev_b32_e32 v14, 16, v12
	v_and_b32_e32 v15, 0xffff0000, v12
	v_mul_f32_e32 v12, 0xbfb8aa3b, v14
	v_exp_f32_e32 v12, v12
	s_nop 0
	v_add_f32_e32 v12, 1.0, v12
	v_rcp_f32_e32 v16, v12
	v_mul_f32_e32 v12, 0xbfb8aa3b, v15
	v_exp_f32_e32 v12, v12
	s_nop 0
	v_add_f32_e32 v12, 1.0, v12
	v_rcp_f32_e32 v17, v12
	v_lshlrev_b32_e32 v12, 16, v13
	v_and_b32_e32 v13, 0xffff0000, v13
	v_pk_mul_f32 v[14:15], v[16:17], v[14:15]
	s_nop 0
	v_pk_mul_f32 v[8:9], v[8:9], v[14:15]
	s_nop 0
	v_cvt_pk_bf16_f32 v8, v8, v9
	v_mul_f32_e32 v9, 0xbfb8aa3b, v12
	v_exp_f32_e32 v9, v9
	s_nop 0
	v_add_f32_e32 v9, 1.0, v9
	v_rcp_f32_e32 v14, v9
	v_mul_f32_e32 v9, 0xbfb8aa3b, v13
	v_exp_f32_e32 v9, v9
	s_nop 0
	v_add_f32_e32 v9, 1.0, v9
	v_rcp_f32_e32 v15, v9
	s_nop 0
	v_pk_mul_f32 v[12:13], v[14:15], v[12:13]
	s_nop 0
	v_pk_mul_f32 v[10:11], v[10:11], v[12:13]
	s_nop 0
	v_cvt_pk_bf16_f32 v9, v10, v11
	global_store_dwordx2 v[30:31], v[8:9], off offset:160
	s_waitcnt vmcnt(1)
	v_mov_b32_e32 v8, v72
	v_mov_b32_e32 v9, v73
	v_lshlrev_b32_e32 v10, 16, v8
	v_and_b32_e32 v11, 0xffff0000, v8
	v_mul_f32_e32 v8, 0xbfb8aa3b, v10
	v_exp_f32_e32 v8, v8
	s_nop 0
	v_add_f32_e32 v8, 1.0, v8
	v_rcp_f32_e32 v12, v8
	v_mul_f32_e32 v8, 0xbfb8aa3b, v11
	v_exp_f32_e32 v8, v8
	s_nop 0
	v_add_f32_e32 v8, 1.0, v8
	v_rcp_f32_e32 v13, v8
	v_lshlrev_b32_e32 v8, 16, v9
	v_and_b32_e32 v9, 0xffff0000, v9
	v_pk_mul_f32 v[10:11], v[12:13], v[10:11]
	s_nop 0
	v_pk_mul_f32 v[4:5], v[4:5], v[10:11]
	s_nop 0
	v_cvt_pk_bf16_f32 v4, v4, v5
	v_mul_f32_e32 v5, 0xbfb8aa3b, v8
	v_exp_f32_e32 v5, v5
	s_nop 0
	v_add_f32_e32 v5, 1.0, v5
	v_rcp_f32_e32 v10, v5
	v_mul_f32_e32 v5, 0xbfb8aa3b, v9
	v_exp_f32_e32 v5, v5
	s_nop 0
	v_add_f32_e32 v5, 1.0, v5
	v_rcp_f32_e32 v11, v5
	s_nop 0
	v_pk_mul_f32 v[8:9], v[10:11], v[8:9]
	s_nop 0
	v_pk_mul_f32 v[6:7], v[6:7], v[8:9]
	s_nop 0
	v_cvt_pk_bf16_f32 v5, v6, v7
	global_store_dwordx2 v[30:31], v[4:5], off offset:192
	s_waitcnt vmcnt(0)
	v_mov_b32_e32 v4, v74
	v_mov_b32_e32 v5, v75
	v_lshlrev_b32_e32 v6, 16, v4
	v_and_b32_e32 v7, 0xffff0000, v4
	v_mul_f32_e32 v4, 0xbfb8aa3b, v6
	v_exp_f32_e32 v4, v4
	s_nop 0
	v_add_f32_e32 v4, 1.0, v4
	v_rcp_f32_e32 v8, v4
	v_mul_f32_e32 v4, 0xbfb8aa3b, v7
	v_exp_f32_e32 v4, v4
	s_nop 0
	v_add_f32_e32 v4, 1.0, v4
	v_rcp_f32_e32 v9, v4
	v_lshlrev_b32_e32 v4, 16, v5
	v_and_b32_e32 v5, 0xffff0000, v5
	v_pk_mul_f32 v[6:7], v[8:9], v[6:7]
	s_nop 0
	v_pk_mul_f32 v[0:1], v[0:1], v[6:7]
	s_nop 0
	v_cvt_pk_bf16_f32 v0, v0, v1
	v_mul_f32_e32 v1, 0xbfb8aa3b, v4
	v_exp_f32_e32 v1, v1
	s_nop 0
	v_add_f32_e32 v1, 1.0, v1
	v_rcp_f32_e32 v6, v1
	v_mul_f32_e32 v1, 0xbfb8aa3b, v5
	v_exp_f32_e32 v1, v1
	s_nop 0
	v_add_f32_e32 v1, 1.0, v1
	v_rcp_f32_e32 v7, v1
	s_nop 0
	v_pk_mul_f32 v[4:5], v[6:7], v[4:5]
	s_nop 0
	v_pk_mul_f32 v[2:3], v[2:3], v[4:5]
	s_nop 0
	v_cvt_pk_bf16_f32 v1, v2, v3
	global_store_dwordx2 v[30:31], v[0:1], off offset:224
	s_cbranch_scc1 .LBB0_527

; DI float lo16(unsigned u) { return __uint_as_float(u << 16); }
; DI float hi16(unsigned u) { return __uint_as_float(u & 0xFFFF0000u); }
; DI int osgpr(int v) { asm volatile("" : "+s"(v)); return v; }
; DI void post_phase(const P& p, int l, unsigned char* smem, int t0, int t1, int bstart, int bstride) {
;     ...
;     for (int rt = t0 + osgpr(bstart); rt < t1; rt += bstride) {
;       for (int rr = 0; rr < 2; ++rr) {
;         const int row = rt * 16 + wave * 2 + rr;
;         const int mr = row < NLAT ? (row >> 11) : 4;
;         const float* h = l == 0 ? (row < NLAT ? p.x + (size_t)row * DM : p.ctx + (size_t)(row - NLAT) * DM) : p.out + (size_t)row * DM;
;         float* hdst = row < NLAT ? p.out + (size_t)row * DM : hc + (size_t)(row - NLAT) * DM;
;         f32x4 y[8]; float ss = 0.f;
; #pragma unroll
;         for (int i = 0; i < 8; ++i) {
;             const u32x2 w = __builtin_nontemporal_load((const u32x2*)(yo + (size_t)row * DM + i * 256 + lane * 4));
;             y[i] = (f32x4){lo16(w.x), hi16(w.x), lo16(w.y), hi16(w.y)};
;             ss += y[i][0] * y[i][0] + y[i][1] * y[i][1] + y[i][2] * y[i][2] + y[i][3] * y[i][3];
;         }
.Lp1_tile:
	s_lshl_b32 s12, s2, 4
	s_add_u32 s12, s12, s11
	s_lshl_b32 s14, s12, 12
	s_add_u32 s14, s14, 0x6c3c000
	s_add_u32 s14, s4, s14
	s_addc_u32 s15, s5, 0
	s_lshl_b32 s16, s12, 13
	s_add_u32 s16, s6, s16
	s_addc_u32 s17, s7, 0
	s_add_u32 s18, s16, 0x2000
	s_addc_u32 s19, s17, 0
	s_lshr_b32 s20, s12, 11
	s_add_u32 s20, s20, 5
	s_mul_i32 s20, s20, 0x6000
	s_add_u32 s20, s20, 0x4804000
	s_add_u32 s20, s4, s20
	s_addc_u32 s21, s5, 0
	global_load_dwordx2 v[52:53], v2, s[14:15] offset:0 nt
	global_load_dwordx2 v[54:55], v2, s[14:15] offset:512 nt
	global_load_dwordx2 v[56:57], v2, s[14:15] offset:1024 nt
	global_load_dwordx2 v[58:59], v2, s[14:15] offset:1536 nt
	global_load_dwordx2 v[60:61], v2, s[14:15] offset:2048 nt
	global_load_dwordx2 v[62:63], v2, s[14:15] offset:2560 nt
	global_load_dwordx2 v[64:65], v2, s[14:15] offset:3072 nt
	global_load_dwordx2 v[66:67], v2, s[14:15] offset:3584 nt
	global_load_dwordx2 v[68:69], v17, s[14:15] offset:0 nt
	global_load_dwordx2 v[70:71], v17, s[14:15] offset:512 nt
	global_load_dwordx2 v[72:73], v17, s[14:15] offset:1024 nt
	global_load_dwordx2 v[74:75], v17, s[14:15] offset:1536 nt
	global_load_dwordx2 v[76:77], v17, s[14:15] offset:2048 nt
	global_load_dwordx2 v[78:79], v17, s[14:15] offset:2560 nt
	global_load_dwordx2 v[80:81], v17, s[14:15] offset:3072 nt
	global_load_dwordx2 v[82:83], v17, s[14:15] offset:3584 nt
	global_load_dwordx4 v[84:87], v0, s[16:17] offset:0 nt
	global_load_dwordx4 v[116:119], v0, s[20:21] offset:0
	global_load_dwordx4 v[88:91], v0, s[16:17] offset:1024 nt
	global_load_dwordx4 v[120:123], v0, s[20:21] offset:1024
	global_load_dwordx4 v[92:95], v0, s[16:17] offset:2048 nt
	global_load_dwordx4 v[124:127], v0, s[20:21] offset:2048
	global_load_dwordx4 v[96:99], v0, s[16:17] offset:3072 nt
	global_load_dwordx4 v[128:131], v0, s[20:21] offset:3072
	global_load_dwordx4 v[100:103], v1, s[16:17] offset:0 nt
	global_load_dwordx4 v[132:135], v1, s[20:21] offset:0
	global_load_dwordx4 v[104:107], v1, s[16:17] offset:1024 nt
	global_load_dwordx4 v[136:139], v1, s[20:21] offset:1024
	global_load_dwordx4 v[108:111], v1, s[16:17] offset:2048 nt
	global_load_dwordx4 v[140:143], v1, s[20:21] offset:2048
	global_load_dwordx4 v[112:115], v1, s[16:17] offset:3072 nt
	global_load_dwordx4 v[144:147], v1, s[20:21] offset:3072
	global_load_dwordx4 v[148:151], v0, s[18:19] offset:0 nt
	global_load_dwordx4 v[152:155], v0, s[18:19] offset:1024 nt
	global_load_dwordx4 v[156:159], v0, s[18:19] offset:2048 nt
	global_load_dwordx4 v[160:163], v0, s[18:19] offset:3072 nt
	global_load_dwordx4 v[164:167], v1, s[18:19] offset:0 nt
	global_load_dwordx4 v[168:171], v1, s[18:19] offset:1024 nt
	global_load_dwordx4 v[172:175], v1, s[18:19] offset:2048 nt
	global_load_dwordx4 v[176:179], v1, s[18:19] offset:3072 nt
	s_waitcnt vmcnt(24)
	v_lshlrev_b32_e32 v212, 16, v52
	v_and_b32_e32 v213, 0xffff0000, v52
	v_lshlrev_b32_e32 v214, 16, v53
	v_and_b32_e32 v215, 0xffff0000, v53
	v_mul_f32_e32 v9, v212, v212
	v_mul_f32_e32 v15, v213, v213
	v_fmac_f32_e32 v9, v214, v214
	v_fmac_f32_e32 v15, v215, v215
	v_lshlrev_b32_e32 v212, 16, v54
	v_and_b32_e32 v213, 0xffff0000, v54
	v_lshlrev_b32_e32 v214, 16, v55
	v_and_b32_e32 v215, 0xffff0000, v55
	v_fmac_f32_e32 v9, v212, v212
	v_fmac_f32_e32 v15, v213, v213
	v_fmac_f32_e32 v9, v214, v214
	v_fmac_f32_e32 v15, v215, v215
	v_lshlrev_b32_e32 v212, 16, v56
	v_and_b32_e32 v213, 0xffff0000, v56
	v_lshlrev_b32_e32 v214, 16, v57
	v_and_b32_e32 v215, 0xffff0000, v57
	v_fmac_f32_e32 v9, v212, v212
	v_fmac_f32_e32 v15, v213, v213
	v_fmac_f32_e32 v9, v214, v214
	v_fmac_f32_e32 v15, v215, v215
	v_lshlrev_b32_e32 v212, 16, v58
	v_and_b32_e32 v213, 0xffff0000, v58
	v_lshlrev_b32_e32 v214, 16, v59
	v_and_b32_e32 v215, 0xffff0000, v59
	v_fmac_f32_e32 v9, v212, v212
	v_fmac_f32_e32 v15, v213, v213
	v_fmac_f32_e32 v9, v214, v214
	v_fmac_f32_e32 v15, v215, v215
	v_lshlrev_b32_e32 v212, 16, v60
	v_and_b32_e32 v213, 0xffff0000, v60
	v_lshlrev_b32_e32 v214, 16, v61
	v_and_b32_e32 v215, 0xffff0000, v61
	v_fmac_f32_e32 v9, v212, v212
	v_fmac_f32_e32 v15, v213, v213
	v_fmac_f32_e32 v9, v214, v214
	v_fmac_f32_e32 v15, v215, v215
	v_lshlrev_b32_e32 v212, 16, v62
	v_and_b32_e32 v213, 0xffff0000, v62
	v_lshlrev_b32_e32 v214, 16, v63
	v_and_b32_e32 v215, 0xffff0000, v63
	v_fmac_f32_e32 v9, v212, v212
	v_fmac_f32_e32 v15, v213, v213
	v_fmac_f32_e32 v9, v214, v214
	v_fmac_f32_e32 v15, v215, v215
	v_lshlrev_b32_e32 v212, 16, v64
	v_and_b32_e32 v213, 0xffff0000, v64
	v_lshlrev_b32_e32 v214, 16, v65
	v_and_b32_e32 v215, 0xffff0000, v65
	v_fmac_f32_e32 v9, v212, v212
	v_fmac_f32_e32 v15, v213, v213
	v_fmac_f32_e32 v9, v214, v214
	v_fmac_f32_e32 v15, v215, v215
	v_lshlrev_b32_e32 v212, 16, v66
	v_and_b32_e32 v213, 0xffff0000, v66
	v_lshlrev_b32_e32 v214, 16, v67
	v_and_b32_e32 v215, 0xffff0000, v67
	v_fmac_f32_e32 v9, v212, v212
	v_fmac_f32_e32 v15, v213, v213
	v_fmac_f32_e32 v9, v214, v214
	v_fmac_f32_e32 v15, v215, v215
	v_add_f32_e32 v9, v9, v15
	v_lshlrev_b32_e32 v212, 16, v68
	v_and_b32_e32 v213, 0xffff0000, v68
	v_lshlrev_b32_e32 v214, 16, v69
	v_and_b32_e32 v215, 0xffff0000, v69
	v_mul_f32_e32 v10, v212, v212
	v_mul_f32_e32 v16, v213, v213
	v_fmac_f32_e32 v10, v214, v214
	v_fmac_f32_e32 v16, v215, v215
	v_lshlrev_b32_e32 v212, 16, v70
	v_and_b32_e32 v213, 0xffff0000, v70
	v_lshlrev_b32_e32 v214, 16, v71
	v_and_b32_e32 v215, 0xffff0000, v71
	v_fmac_f32_e32 v10, v212, v212
	v_fmac_f32_e32 v16, v213, v213
	v_fmac_f32_e32 v10, v214, v214
	v_fmac_f32_e32 v16, v215, v215
	v_lshlrev_b32_e32 v212, 16, v72
	v_and_b32_e32 v213, 0xffff0000, v72
	v_lshlrev_b32_e32 v214, 16, v73
	v_and_b32_e32 v215, 0xffff0000, v73
; DI void post_phase(const P& p, int l, unsigned char* smem, int t0, int t1, int bstart, int bstride) {
;     ...
;         ss = wave_sum(ss);
;         const float rstd = rsqrtf(ss * (1.f / 2048.f) + 1e-6f);
;         const float* md = mod + (size_t)(l * 5 + mr) * 6144;
;         float ss2 = 0.f;
; #pragma unroll
;         for (int i = 0; i < 8; ++i) {
;             const int j = i * 256 + lane * 4;
;             const f32x4 hv = __builtin_nontemporal_load((const f32x4*)(h + j)), gt = *(const f32x4*)(md + 4096 + j), nw = *(const f32x4*)(p.norm_post + l * DM + j);
; #pragma unroll
;             for (int e = 0; e < 4; ++e) { y[i][e] = hv[e] + gt[e] * (y[i][e] * rstd * nw[e]); ss2 += y[i][e] * y[i][e]; }
;             __builtin_nontemporal_store(y[i], (f32x4*)(hdst + j));
	v_fmac_f32_e32 v10, v212, v212
	v_fmac_f32_e32 v16, v213, v213
	v_fmac_f32_e32 v10, v214, v214
	v_fmac_f32_e32 v16, v215, v215
	v_lshlrev_b32_e32 v212, 16, v74
	v_and_b32_e32 v213, 0xffff0000, v74
	v_lshlrev_b32_e32 v214, 16, v75
	v_and_b32_e32 v215, 0xffff0000, v75
	v_fmac_f32_e32 v10, v212, v212
	v_fmac_f32_e32 v16, v213, v213
	v_fmac_f32_e32 v10, v214, v214
	v_fmac_f32_e32 v16, v215, v215
	v_lshlrev_b32_e32 v212, 16, v76
	v_and_b32_e32 v213, 0xffff0000, v76
	v_lshlrev_b32_e32 v214, 16, v77
	v_and_b32_e32 v215, 0xffff0000, v77
	v_fmac_f32_e32 v10, v212, v212
	v_fmac_f32_e32 v16, v213, v213
	v_fmac_f32_e32 v10, v214, v214
	v_fmac_f32_e32 v16, v215, v215
	v_lshlrev_b32_e32 v212, 16, v78
	v_and_b32_e32 v213, 0xffff0000, v78
	v_lshlrev_b32_e32 v214, 16, v79
	v_and_b32_e32 v215, 0xffff0000, v79
	v_fmac_f32_e32 v10, v212, v212
	v_fmac_f32_e32 v16, v213, v213
	v_fmac_f32_e32 v10, v214, v214
	v_fmac_f32_e32 v16, v215, v215
	v_lshlrev_b32_e32 v212, 16, v80
	v_and_b32_e32 v213, 0xffff0000, v80
	v_lshlrev_b32_e32 v214, 16, v81
	v_and_b32_e32 v215, 0xffff0000, v81
	v_fmac_f32_e32 v10, v212, v212
	v_fmac_f32_e32 v16, v213, v213
	v_fmac_f32_e32 v10, v214, v214
	v_fmac_f32_e32 v16, v215, v215
	v_lshlrev_b32_e32 v212, 16, v82
	v_and_b32_e32 v213, 0xffff0000, v82
	v_lshlrev_b32_e32 v214, 16, v83
	v_and_b32_e32 v215, 0xffff0000, v83
	v_fmac_f32_e32 v10, v212, v212
	v_fmac_f32_e32 v16, v213, v213
	v_fmac_f32_e32 v10, v214, v214
	v_fmac_f32_e32 v16, v215, v215
	v_add_f32_e32 v10, v10, v16
	ds_bpermute_b32 v11, v3, v9
	ds_bpermute_b32 v12, v3, v10
	s_waitcnt lgkmcnt(1)
	v_add_f32_e32 v9, v9, v11
	s_waitcnt lgkmcnt(0)
	v_add_f32_e32 v10, v10, v12
	ds_bpermute_b32 v11, v4, v9
	ds_bpermute_b32 v12, v4, v10
	s_waitcnt lgkmcnt(1)
	v_add_f32_e32 v9, v9, v11
	s_waitcnt lgkmcnt(0)
	v_add_f32_e32 v10, v10, v12
	ds_bpermute_b32 v11, v5, v9
	ds_bpermute_b32 v12, v5, v10
	s_waitcnt lgkmcnt(1)
	v_add_f32_e32 v9, v9, v11
	s_waitcnt lgkmcnt(0)
	v_add_f32_e32 v10, v10, v12
	ds_bpermute_b32 v11, v6, v9
	ds_bpermute_b32 v12, v6, v10
	s_waitcnt lgkmcnt(1)
	v_add_f32_e32 v9, v9, v11
	s_waitcnt lgkmcnt(0)
	v_add_f32_e32 v10, v10, v12
	ds_bpermute_b32 v11, v7, v9
	ds_bpermute_b32 v12, v7, v10
	s_waitcnt lgkmcnt(1)
	v_add_f32_e32 v9, v9, v11
	s_waitcnt lgkmcnt(0)
	v_add_f32_e32 v10, v10, v12
	ds_bpermute_b32 v11, v8, v9
	ds_bpermute_b32 v12, v8, v10
	s_waitcnt lgkmcnt(1)
	v_add_f32_e32 v9, v9, v11
	s_waitcnt lgkmcnt(0)
	v_add_f32_e32 v10, v10, v12
	v_mov_b32_e32 v11, 0x358637bd
	v_fmamk_f32 v9, v9, 0x3a000000, v11
	v_fmamk_f32 v10, v10, 0x3a000000, v11
	v_rsq_f32_e32 v13, v9
	v_rsq_f32_e32 v14, v10
	s_nop 0
	v_lshlrev_b32_e32 v212, 16, v52
	v_and_b32_e32 v213, 0xffff0000, v52
	v_lshlrev_b32_e32 v214, 16, v53
	v_and_b32_e32 v215, 0xffff0000, v53
	v_mul_f32_e32 v212, v13, v212
	v_mul_f32_e32 v213, v13, v213
	v_mul_f32_e32 v214, v13, v214
	v_mul_f32_e32 v215, v13, v215
	v_mul_f32_e32 v212, v20, v212
	v_mul_f32_e32 v213, v21, v213
	v_mul_f32_e32 v214, v22, v214
	v_mul_f32_e32 v215, v23, v215
	s_waitcnt vmcnt(22)
	v_fma_f32 v84, v116, v212, v84
	v_fma_f32 v85, v117, v213, v85
	v_fma_f32 v86, v118, v214, v86
	v_fma_f32 v87, v119, v215, v87
	global_store_dwordx4 v0, v[84:87], s[16:17] offset:0 nt
	v_lshlrev_b32_e32 v212, 16, v54
	v_and_b32_e32 v213, 0xffff0000, v54
	v_lshlrev_b32_e32 v214, 16, v55
	v_and_b32_e32 v215, 0xffff0000, v55
	v_mul_f32_e32 v212, v13, v212
	v_mul_f32_e32 v213, v13, v213
	v_mul_f32_e32 v214, v13, v214
	v_mul_f32_e32 v215, v13, v215
	v_mul_f32_e32 v212, v24, v212
	v_mul_f32_e32 v213, v25, v213
	v_mul_f32_e32 v214, v26, v214
	v_mul_f32_e32 v215, v27, v215
	s_waitcnt vmcnt(20)
	v_fma_f32 v88, v120, v212, v88
	v_fma_f32 v89, v121, v213, v89
	v_fma_f32 v90, v122, v214, v90
	v_fma_f32 v91, v123, v215, v91
	global_store_dwordx4 v0, v[88:91], s[16:17] offset:1024 nt
	v_lshlrev_b32_e32 v212, 16, v56
	v_and_b32_e32 v213, 0xffff0000, v56
	v_lshlrev_b32_e32 v214, 16, v57
	v_and_b32_e32 v215, 0xffff0000, v57
	v_mul_f32_e32 v212, v13, v212
	v_mul_f32_e32 v213, v13, v213
	v_mul_f32_e32 v214, v13, v214
	v_mul_f32_e32 v215, v13, v215
	v_mul_f32_e32 v212, v28, v212
	v_mul_f32_e32 v213, v29, v213
	v_mul_f32_e32 v214, v30, v214
	v_mul_f32_e32 v215, v31, v215
	s_waitcnt vmcnt(18)
	v_fma_f32 v92, v124, v212, v92
	v_fma_f32 v93, v125, v213, v93
	v_fma_f32 v94, v126, v214, v94
	v_fma_f32 v95, v127, v215, v95
	global_store_dwordx4 v0, v[92:95], s[16:17] offset:2048 nt
	v_lshlrev_b32_e32 v212, 16, v58
	v_and_b32_e32 v213, 0xffff0000, v58
	v_lshlrev_b32_e32 v214, 16, v59
	v_and_b32_e32 v215, 0xffff0000, v59
	v_mul_f32_e32 v212, v13, v212
	v_mul_f32_e32 v213, v13, v213
	v_mul_f32_e32 v214, v13, v214
	v_mul_f32_e32 v215, v13, v215
	v_mul_f32_e32 v212, v32, v212
	v_mul_f32_e32 v213, v33, v213
	v_mul_f32_e32 v214, v34, v214
	v_mul_f32_e32 v215, v35, v215
	s_waitcnt vmcnt(16)
	v_fma_f32 v96, v128, v212, v96
	v_fma_f32 v97, v129, v213, v97
	v_fma_f32 v98, v130, v214, v98
	v_fma_f32 v99, v131, v215, v99
	global_store_dwordx4 v0, v[96:99], s[16:17] offset:3072 nt
	v_lshlrev_b32_e32 v212, 16, v60
	v_and_b32_e32 v213, 0xffff0000, v60
	v_lshlrev_b32_e32 v214, 16, v61
	v_and_b32_e32 v215, 0xffff0000, v61
	v_mul_f32_e32 v212, v13, v212
	v_mul_f32_e32 v213, v13, v213
	v_mul_f32_e32 v214, v13, v214
	v_mul_f32_e32 v215, v13, v215
	v_mul_f32_e32 v212, v36, v212
	v_mul_f32_e32 v213, v37, v213
	v_mul_f32_e32 v214, v38, v214
	v_mul_f32_e32 v215, v39, v215
	s_waitcnt vmcnt(14)
; DI int osgpr(int v) { asm volatile("" : "+s"(v)); return v; }
; DI void post_phase(const P& p, int l, unsigned char* smem, int t0, int t1, int bstart, int bstride) {
;     ...
;     for (int rt = t0 + osgpr(bstart); rt < t1; rt += bstride) {
;     ...
;         for (int i = 0; i < 8; ++i) {
;             const int j = i * 256 + lane * 4;
;             const f32x4 hv = __builtin_nontemporal_load((const f32x4*)(h + j)), gt = *(const f32x4*)(md + 4096 + j), nw = *(const f32x4*)(p.norm_post + l * DM + j);
; #pragma unroll
;             for (int e = 0; e < 4; ++e) { y[i][e] = hv[e] + gt[e] * (y[i][e] * rstd * nw[e]); ss2 += y[i][e] * y[i][e]; }
;             __builtin_nontemporal_store(y[i], (f32x4*)(hdst + j));
	v_fma_f32 v100, v132, v212, v100
	v_fma_f32 v101, v133, v213, v101
	v_fma_f32 v102, v134, v214, v102
	v_fma_f32 v103, v135, v215, v103
	global_store_dwordx4 v1, v[100:103], s[16:17] offset:0 nt
	v_lshlrev_b32_e32 v212, 16, v62
	v_and_b32_e32 v213, 0xffff0000, v62
	v_lshlrev_b32_e32 v214, 16, v63
	v_and_b32_e32 v215, 0xffff0000, v63
	v_mul_f32_e32 v212, v13, v212
	v_mul_f32_e32 v213, v13, v213
	v_mul_f32_e32 v214, v13, v214
	v_mul_f32_e32 v215, v13, v215
	v_mul_f32_e32 v212, v40, v212
	v_mul_f32_e32 v213, v41, v213
	v_mul_f32_e32 v214, v42, v214
	v_mul_f32_e32 v215, v43, v215
	s_waitcnt vmcnt(12)
	v_fma_f32 v104, v136, v212, v104
	v_fma_f32 v105, v137, v213, v105
	v_fma_f32 v106, v138, v214, v106
	v_fma_f32 v107, v139, v215, v107
	global_store_dwordx4 v1, v[104:107], s[16:17] offset:1024 nt
	v_lshlrev_b32_e32 v212, 16, v64
	v_and_b32_e32 v213, 0xffff0000, v64
	v_lshlrev_b32_e32 v214, 16, v65
	v_and_b32_e32 v215, 0xffff0000, v65
	v_mul_f32_e32 v212, v13, v212
	v_mul_f32_e32 v213, v13, v213
	v_mul_f32_e32 v214, v13, v214
	v_mul_f32_e32 v215, v13, v215
	v_mul_f32_e32 v212, v44, v212
	v_mul_f32_e32 v213, v45, v213
	v_mul_f32_e32 v214, v46, v214
	v_mul_f32_e32 v215, v47, v215
	s_waitcnt vmcnt(10)
	v_fma_f32 v108, v140, v212, v108
	v_fma_f32 v109, v141, v213, v109
	v_fma_f32 v110, v142, v214, v110
	v_fma_f32 v111, v143, v215, v111
	global_store_dwordx4 v1, v[108:111], s[16:17] offset:2048 nt
	v_lshlrev_b32_e32 v212, 16, v66
	v_and_b32_e32 v213, 0xffff0000, v66
	v_lshlrev_b32_e32 v214, 16, v67
	v_and_b32_e32 v215, 0xffff0000, v67
	v_mul_f32_e32 v212, v13, v212
	v_mul_f32_e32 v213, v13, v213
	v_mul_f32_e32 v214, v13, v214
	v_mul_f32_e32 v215, v13, v215
	v_mul_f32_e32 v212, v48, v212
	v_mul_f32_e32 v213, v49, v213
	v_mul_f32_e32 v214, v50, v214
	v_mul_f32_e32 v215, v51, v215
	s_waitcnt vmcnt(8)
	v_fma_f32 v112, v144, v212, v112
	v_fma_f32 v113, v145, v213, v113
	v_fma_f32 v114, v146, v214, v114
	v_fma_f32 v115, v147, v215, v115
	global_store_dwordx4 v1, v[112:115], s[16:17] offset:3072 nt
	v_lshlrev_b32_e32 v212, 16, v68
	v_and_b32_e32 v213, 0xffff0000, v68
	v_lshlrev_b32_e32 v214, 16, v69
	v_and_b32_e32 v215, 0xffff0000, v69
	v_mul_f32_e32 v212, v14, v212
	v_mul_f32_e32 v213, v14, v213
	v_mul_f32_e32 v214, v14, v214
	v_mul_f32_e32 v215, v14, v215
	v_mul_f32_e32 v212, v20, v212
	v_mul_f32_e32 v213, v21, v213
	v_mul_f32_e32 v214, v22, v214
	v_mul_f32_e32 v215, v23, v215
	s_waitcnt vmcnt(7)
	v_fma_f32 v148, v116, v212, v148
	v_fma_f32 v149, v117, v213, v149
	v_fma_f32 v150, v118, v214, v150
	v_fma_f32 v151, v119, v215, v151
	global_store_dwordx4 v0, v[148:151], s[18:19] offset:0 nt
	v_lshlrev_b32_e32 v212, 16, v70
	v_and_b32_e32 v213, 0xffff0000, v70
	v_lshlrev_b32_e32 v214, 16, v71
	v_and_b32_e32 v215, 0xffff0000, v71
	v_mul_f32_e32 v212, v14, v212
	v_mul_f32_e32 v213, v14, v213
	v_mul_f32_e32 v214, v14, v214
	v_mul_f32_e32 v215, v14, v215
	v_mul_f32_e32 v212, v24, v212
	v_mul_f32_e32 v213, v25, v213
	v_mul_f32_e32 v214, v26, v214
	v_mul_f32_e32 v215, v27, v215
	s_waitcnt vmcnt(6)
	v_fma_f32 v152, v120, v212, v152
	v_fma_f32 v153, v121, v213, v153
	v_fma_f32 v154, v122, v214, v154
	v_fma_f32 v155, v123, v215, v155
	global_store_dwordx4 v0, v[152:155], s[18:19] offset:1024 nt
	v_lshlrev_b32_e32 v212, 16, v72
	v_and_b32_e32 v213, 0xffff0000, v72
	v_lshlrev_b32_e32 v214, 16, v73
	v_and_b32_e32 v215, 0xffff0000, v73
	v_mul_f32_e32 v212, v14, v212
	v_mul_f32_e32 v213, v14, v213
	v_mul_f32_e32 v214, v14, v214
	v_mul_f32_e32 v215, v14, v215
	v_mul_f32_e32 v212, v28, v212
	v_mul_f32_e32 v213, v29, v213
	v_mul_f32_e32 v214, v30, v214
	v_mul_f32_e32 v215, v31, v215
	s_waitcnt vmcnt(5)
	v_fma_f32 v156, v124, v212, v156
	v_fma_f32 v157, v125, v213, v157
	v_fma_f32 v158, v126, v214, v158
	v_fma_f32 v159, v127, v215, v159
	global_store_dwordx4 v0, v[156:159], s[18:19] offset:2048 nt
	v_lshlrev_b32_e32 v212, 16, v74
	v_and_b32_e32 v213, 0xffff0000, v74
	v_lshlrev_b32_e32 v214, 16, v75
	v_and_b32_e32 v215, 0xffff0000, v75
	v_mul_f32_e32 v212, v14, v212
	v_mul_f32_e32 v213, v14, v213
	v_mul_f32_e32 v214, v14, v214
	v_mul_f32_e32 v215, v14, v215
	v_mul_f32_e32 v212, v32, v212
	v_mul_f32_e32 v213, v33, v213
	v_mul_f32_e32 v214, v34, v214
	v_mul_f32_e32 v215, v35, v215
	s_waitcnt vmcnt(4)
	v_fma_f32 v160, v128, v212, v160
	v_fma_f32 v161, v129, v213, v161
	v_fma_f32 v162, v130, v214, v162
	v_fma_f32 v163, v131, v215, v163
	global_store_dwordx4 v0, v[160:163], s[18:19] offset:3072 nt
	v_lshlrev_b32_e32 v212, 16, v76
	v_and_b32_e32 v213, 0xffff0000, v76
	v_lshlrev_b32_e32 v214, 16, v77
	v_and_b32_e32 v215, 0xffff0000, v77
	v_mul_f32_e32 v212, v14, v212
	v_mul_f32_e32 v213, v14, v213
	v_mul_f32_e32 v214, v14, v214
	v_mul_f32_e32 v215, v14, v215
	v_mul_f32_e32 v212, v36, v212
	v_mul_f32_e32 v213, v37, v213
	v_mul_f32_e32 v214, v38, v214
	v_mul_f32_e32 v215, v39, v215
	s_waitcnt vmcnt(3)
	v_fma_f32 v164, v132, v212, v164
	v_fma_f32 v165, v133, v213, v165
	v_fma_f32 v166, v134, v214, v166
	v_fma_f32 v167, v135, v215, v167
	global_store_dwordx4 v1, v[164:167], s[18:19] offset:0 nt
	v_lshlrev_b32_e32 v212, 16, v78
	v_and_b32_e32 v213, 0xffff0000, v78
	v_lshlrev_b32_e32 v214, 16, v79
	v_and_b32_e32 v215, 0xffff0000, v79
	v_mul_f32_e32 v212, v14, v212
	v_mul_f32_e32 v213, v14, v213
	v_mul_f32_e32 v214, v14, v214
	v_mul_f32_e32 v215, v14, v215
	v_mul_f32_e32 v212, v40, v212
	v_mul_f32_e32 v213, v41, v213
	v_mul_f32_e32 v214, v42, v214
	v_mul_f32_e32 v215, v43, v215
	s_waitcnt vmcnt(2)
	v_fma_f32 v168, v136, v212, v168
	v_fma_f32 v169, v137, v213, v169
	v_fma_f32 v170, v138, v214, v170
	v_fma_f32 v171, v139, v215, v171
	global_store_dwordx4 v1, v[168:171], s[18:19] offset:1024 nt
	v_lshlrev_b32_e32 v212, 16, v80
	v_and_b32_e32 v213, 0xffff0000, v80
	v_lshlrev_b32_e32 v214, 16, v81
	v_and_b32_e32 v215, 0xffff0000, v81
	v_mul_f32_e32 v212, v14, v212
	v_mul_f32_e32 v213, v14, v213
	v_mul_f32_e32 v214, v14, v214
	v_mul_f32_e32 v215, v14, v215
	v_mul_f32_e32 v212, v44, v212
	v_mul_f32_e32 v213, v45, v213
	v_mul_f32_e32 v214, v46, v214
	v_mul_f32_e32 v215, v47, v215
	s_waitcnt vmcnt(1)
	v_fma_f32 v172, v140, v212, v172
	v_fma_f32 v173, v141, v213, v173
	v_fma_f32 v174, v142, v214, v174
	v_fma_f32 v175, v143, v215, v175
	global_store_dwordx4 v1, v[172:175], s[18:19] offset:2048 nt
	v_lshlrev_b32_e32 v212, 16, v82
	v_and_b32_e32 v213, 0xffff0000, v82
	v_lshlrev_b32_e32 v214, 16, v83
	v_and_b32_e32 v215, 0xffff0000, v83
	v_mul_f32_e32 v212, v14, v212
	v_mul_f32_e32 v213, v14, v213
	v_mul_f32_e32 v214, v14, v214
	v_mul_f32_e32 v215, v14, v215
	v_mul_f32_e32 v212, v48, v212
	v_mul_f32_e32 v213, v49, v213
	v_mul_f32_e32 v214, v50, v214
	v_mul_f32_e32 v215, v51, v215
	s_waitcnt vmcnt(0)
	v_fma_f32 v176, v144, v212, v176
	v_fma_f32 v177, v145, v213, v177
	v_fma_f32 v178, v146, v214, v178
	v_fma_f32 v179, v147, v215, v179
	global_store_dwordx4 v1, v[176:179], s[18:19] offset:3072 nt
	s_add_u32 s2, s2, s10
	s_cmpk_lt_i32 s2, 0x200
	s_cbranch_scc1 .Lp1_tile
	s_branch .LBB0_805

; #define LAS __attribute__((address_space(3)))
; DI int otid() { int t = threadIdx.x; asm volatile("" : "+v"(t)); return t; }
; DI int osgpr(int v) { asm volatile("" : "+s"(v)); return v; }
; #define PHASE_BEGIN P q = p; { size_t z_ = 0; asm volatile("" : "+s"(z_)); q.ws = p.ws + z_; } unsigned char* sm = smem + osgpr(0); const int b1 = osgpr(bid); (void)sm; (void)b1;
; DI void post_phase(const P& p, int l, unsigned char* smem, int t0, int t1, int bstart, int bstride) {
;     const int tid = otid(); const int wave = tid >> 6, lane = tid & 63;
;     const float* mod = (const float*)(p.ws + WS_MOD);
;     bf16_t* nb = (bf16_t*)(p.ws + WS_NBUF);
;     const bf16_t* yo = (const bf16_t*)(p.ws + WS_SBUF);
;     float* hc = (float*)(p.ws + WS_HC);
;     for (int rt = t0 + osgpr(bstart); rt < t1; rt += bstride) {
;       for (int rr = 0; rr < 2; ++rr) {
;         const int row = rt * 16 + wave * 2 + rr;
;         const int mr = row < NLAT ? (row >> 11) : 4;
;         const float* h = l == 0 ? (row < NLAT ? p.x + (size_t)row * DM : p.ctx + (size_t)(row - NLAT) * DM) : p.out + (size_t)row * DM;
;         float* hdst = row < NLAT ? p.out + (size_t)row * DM : hc + (size_t)(row - NLAT) * DM;
;         f32x4 y[8]; float ss = 0.f;
; #pragma unroll
;         for (int i = 0; i < 8; ++i) {
;             const u32x2 w = __builtin_nontemporal_load((const u32x2*)(yo + (size_t)row * DM + i * 256 + lane * 4));
; __global__ __launch_bounds__(512, 2) void mega(P p) {
;     ...
;         if (l == 0) {
;             {
;                 PHASE_BEGIN
;                 if (b1 < 32) {
;                     pg8::Gemm g{(const bf16_t*)(q.ws + WS_YBUF) + (size_t)NLAT * DM, (const bf16_t*)(q.ws + WS_WOUTT), NROW - NLAT, DM, DM};
;                     pg8::StaticOrder so; so.init(g.M, g.N, 32, b1);
;                     pg8::EpiBf16 e{(bf16_t*)(q.ws + WS_SBUF) + (size_t)NLAT * DM, DM};
;                     pg8::gemm_phase((LAS unsigned char*)sm, g, so, e);
;                 } else post_phase(q, 0, sm, 0, NLAT / 16, b1 - 32, nb - 32);
.LBB0_806:
	s_andn2_b64 vcc, exec, s[0:1]
	s_cbranch_vccnz .LBB0_173
	s_mov_b64 s[0:1], 0
	v_readlane_b32 s4, v254, 26
	v_readlane_b32 s5, v254, 27
	s_add_u32 s38, s4, s0
	s_mov_b32 s2, s19
	s_addc_u32 s39, s5, s1
	s_add_i32 s22, s2, 0
	v_readlane_b32 s21, v253, 0
	s_mov_b64 s[8:9], 0x6c3c000
	s_cmp_gt_i32 s21, 31
	s_mov_b64 s[36:37], -1
	v_readlane_b32 s6, v254, 28
	v_readlane_b32 s7, v254, 29
	s_cbranch_scc0 .LBB0_822
	s_sub_i32 s24, s21, 32
	v_mov_b32_e32 v0, v166
	s_cmpk_gt_i32 s24, 0x1ff
	s_cbranch_scc1 .LBB0_821
	s_mov_b32 s98, s24
	v_readlane_b32 s99, v254, 20
	s_movk_i32 s100, 0x200
	s_mov_b32 s101, 0
.Lpost0:
	v_and_b32_e32 v219, 63, v166
	v_lshrrev_b32_e32 v244, 6, v166
	v_lshlrev_b32_e32 v224, 4, v219
	v_lshlrev_b32_e32 v228, 3, v219
	v_readfirstlane_b32 s24, v244
	v_add_u32_e32 v225, 0x1000, v224
	v_add_u32_e32 v226, 0x2000, v224
	v_add_u32_e32 v227, 0x3000, v224
	v_add_u32_e32 v229, 0x1000, v228
	v_xor_b32_e32 v230, 32, v219
	v_xor_b32_e32 v231, 16, v219
	v_xor_b32_e32 v232, 8, v219
	v_xor_b32_e32 v233, 4, v219
	v_xor_b32_e32 v234, 2, v219
	v_xor_b32_e32 v235, 1, v219
	v_lshlrev_b32_e32 v230, 2, v230
	v_lshlrev_b32_e32 v231, 2, v231
	v_lshlrev_b32_e32 v232, 2, v232
	v_lshlrev_b32_e32 v233, 2, v233
	v_lshlrev_b32_e32 v234, 2, v234
	v_lshlrev_b32_e32 v235, 2, v235
	v_and_b32_e32 v245, 15, v219
	v_lshrrev_b32_e32 v246, 4, v219
	v_lshlrev_b32_e32 v212, 12, v245
	v_lshl_add_u32 v212, v244, 9, v212
	v_lshl_add_u32 v212, v246, 4, v212
	v_add_u32_e32 v213, 0x10000, v212
	v_add_u32_e32 v214, 0x20000, v212
	v_mul_u32_u24_e32 v215, 0xc00, v244
	v_mul_u32_u24_e32 v247, 0x300, v246
	v_add_u32_e32 v215, v215, v247
	v_lshl_add_u32 v215, v245, 2, v215
	v_lshlrev_b32_e32 v216, 2, v166
	s_lshl_b32 s24, s24, 1
	v_readlane_b32 s0, v254, 26
	v_readlane_b32 s1, v254, 27
	v_readlane_b32 s2, v254, 16
	v_readlane_b32 s3, v254, 17
	v_readlane_b32 s4, v254, 21
	v_readlane_b32 s5, v254, 22
	s_add_u32 s6, s0, 0x17e7d200
	s_addc_u32 s7, s1, 0
	s_add_u32 s40, s0, 0x17ead200
	s_addc_u32 s41, s1, 0
.Lpost0_tile:
	v_readlane_b32 s44, v254, 37
	v_readlane_b32 s45, v254, 38
	s_add_u32 s46, s0, 0x10e3c000
	s_addc_u32 s47, s1, 0
	s_lshl_b32 s28, s98, 4
	s_add_u32 s28, s28, s24
	s_lshl_b32 s36, s28, 13
	s_sub_u32 s37, s28, 0x2000
	s_lshl_b32 s37, s37, 13
	s_lshr_b32 s48, s28, 11
	s_cmpk_lt_u32 s28, 0x2000
	s_cselect_b32 s42, s92, s90
	s_cselect_b32 s43, s93, s91
	s_cselect_b32 s44, s44, s46
	s_cselect_b32 s45, s45, s47
	s_cselect_b32 s36, s36, s37
	s_cselect_b32 s48, s48, 4
	s_add_u32 s42, s42, s36
	s_addc_u32 s43, s43, 0
	s_add_u32 s44, s44, s36
	s_addc_u32 s45, s45, 0
	s_lshl_b32 s36, s28, 12
	s_add_u32 s37, s36, 0x6c3c000
	s_add_u32 s46, s0, s37
	s_addc_u32 s47, s1, 0
	s_add_u32 s37, s36, 0x483c000
	s_add_u32 s30, s0, s37
	s_addc_u32 s31, s1, 0
	s_mul_i32 s48, s48, 0x6000
	s_add_u32 s37, s48, 0x4804000
	s_add_u32 s26, s0, s37
	s_addc_u32 s27, s1, 0
	s_add_u32 s37, s48, 0x481e000
	s_add_u32 s48, s0, s37
	s_addc_u32 s49, s1, 0
	global_load_dwordx2 v[142:143], v228, s[46:47] offset:0 nt
	global_load_dwordx2 v[144:145], v228, s[46:47] offset:512 nt
	global_load_dwordx2 v[146:147], v228, s[46:47] offset:1024 nt
	global_load_dwordx2 v[148:149], v228, s[46:47] offset:1536 nt
	global_load_dwordx2 v[150:151], v228, s[46:47] offset:2048 nt
	global_load_dwordx2 v[152:153], v228, s[46:47] offset:2560 nt
	global_load_dwordx2 v[154:155], v228, s[46:47] offset:3072 nt
	global_load_dwordx2 v[156:157], v228, s[46:47] offset:3584 nt
	global_load_dwordx2 v[184:185], v229, s[46:47] offset:0 nt
	global_load_dwordx2 v[186:187], v229, s[46:47] offset:512 nt
	global_load_dwordx2 v[188:189], v229, s[46:47] offset:1024 nt
	global_load_dwordx2 v[190:191], v229, s[46:47] offset:1536 nt
	global_load_dwordx2 v[192:193], v229, s[46:47] offset:2048 nt
	global_load_dwordx2 v[194:195], v229, s[46:47] offset:2560 nt
	global_load_dwordx2 v[196:197], v229, s[46:47] offset:3072 nt
	global_load_dwordx2 v[198:199], v229, s[46:47] offset:3584 nt
	global_load_dwordx4 v[96:99], v224, s[2:3] offset:0
	global_load_dwordx4 v[100:103], v224, s[2:3] offset:1024
	global_load_dwordx4 v[104:107], v224, s[2:3] offset:2048
	global_load_dwordx4 v[108:111], v224, s[2:3] offset:3072
	global_load_dwordx4 v[112:115], v225, s[2:3] offset:0
	global_load_dwordx4 v[116:119], v225, s[2:3] offset:1024
	global_load_dwordx4 v[120:123], v225, s[2:3] offset:2048
	global_load_dwordx4 v[124:127], v225, s[2:3] offset:3072
	global_load_dwordx4 v[0:3], v224, s[42:43] offset:0 nt
	global_load_dwordx4 v[64:67], v224, s[26:27] offset:0
	global_load_dwordx4 v[4:7], v224, s[42:43] offset:1024 nt
	global_load_dwordx4 v[68:71], v224, s[26:27] offset:1024
	global_load_dwordx4 v[8:11], v224, s[42:43] offset:2048 nt
	global_load_dwordx4 v[72:75], v224, s[26:27] offset:2048
	global_load_dwordx4 v[12:15], v224, s[42:43] offset:3072 nt
	global_load_dwordx4 v[76:79], v224, s[26:27] offset:3072
	global_load_dwordx4 v[16:19], v225, s[42:43] offset:0 nt
	global_load_dwordx4 v[80:83], v225, s[26:27] offset:0
	global_load_dwordx4 v[20:23], v225, s[42:43] offset:1024 nt
	global_load_dwordx4 v[84:87], v225, s[26:27] offset:1024
	global_load_dwordx4 v[24:27], v225, s[42:43] offset:2048 nt
	global_load_dwordx4 v[88:91], v225, s[26:27] offset:2048
	global_load_dwordx4 v[28:31], v225, s[42:43] offset:3072 nt
	global_load_dwordx4 v[92:95], v225, s[26:27] offset:3072
	global_load_dwordx4 v[32:35], v226, s[42:43] offset:0 nt
	global_load_dwordx4 v[36:39], v226, s[42:43] offset:1024 nt
	global_load_dwordx4 v[40:43], v226, s[42:43] offset:2048 nt
	global_load_dwordx4 v[44:47], v226, s[42:43] offset:3072 nt
	global_load_dwordx4 v[48:51], v227, s[42:43] offset:0 nt
	global_load_dwordx4 v[52:55], v227, s[42:43] offset:1024 nt
	global_load_dwordx4 v[56:59], v227, s[42:43] offset:2048 nt
	global_load_dwordx4 v[60:63], v227, s[42:43] offset:3072 nt
	s_waitcnt vmcnt(32)
; DI float lo16(unsigned u) { return __uint_as_float(u << 16); }
; DI float hi16(unsigned u) { return __uint_as_float(u & 0xFFFF0000u); }
; DI void post_phase(const P& p, int l, unsigned char* smem, int t0, int t1, int bstart, int bstride) {
;     ...
;         f32x4 y[8]; float ss = 0.f;
; #pragma unroll
;         for (int i = 0; i < 8; ++i) {
;             const u32x2 w = __builtin_nontemporal_load((const u32x2*)(yo + (size_t)row * DM + i * 256 + lane * 4));
;             y[i] = (f32x4){lo16(w.x), hi16(w.x), lo16(w.y), hi16(w.y)};
;             ss += y[i][0] * y[i][0] + y[i][1] * y[i][1] + y[i][2] * y[i][2] + y[i][3] * y[i][3];
;         }
;         ss = wave_sum(ss);
	v_lshlrev_b32_e32 v200, 16, v142
	v_and_b32_e32 v201, 0xffff0000, v142
	v_lshlrev_b32_e32 v202, 16, v143
	v_and_b32_e32 v203, 0xffff0000, v143
	v_mul_f32_e32 v236, v200, v200
	v_mul_f32_e32 v237, v201, v201
	v_fmac_f32_e32 v236, v202, v202
	v_fmac_f32_e32 v237, v203, v203
	v_lshlrev_b32_e32 v200, 16, v144
	v_and_b32_e32 v201, 0xffff0000, v144
	v_lshlrev_b32_e32 v202, 16, v145
	v_and_b32_e32 v203, 0xffff0000, v145
	v_fmac_f32_e32 v236, v200, v200
	v_fmac_f32_e32 v237, v201, v201
	v_fmac_f32_e32 v236, v202, v202
	v_fmac_f32_e32 v237, v203, v203
	v_lshlrev_b32_e32 v200, 16, v146
	v_and_b32_e32 v201, 0xffff0000, v146
	v_lshlrev_b32_e32 v202, 16, v147
	v_and_b32_e32 v203, 0xffff0000, v147
	v_fmac_f32_e32 v236, v200, v200
	v_fmac_f32_e32 v237, v201, v201
	v_fmac_f32_e32 v236, v202, v202
	v_fmac_f32_e32 v237, v203, v203
	v_lshlrev_b32_e32 v200, 16, v148
	v_and_b32_e32 v201, 0xffff0000, v148
	v_lshlrev_b32_e32 v202, 16, v149
	v_and_b32_e32 v203, 0xffff0000, v149
	v_fmac_f32_e32 v236, v200, v200
	v_fmac_f32_e32 v237, v201, v201
	v_fmac_f32_e32 v236, v202, v202
	v_fmac_f32_e32 v237, v203, v203
	v_lshlrev_b32_e32 v200, 16, v150
	v_and_b32_e32 v201, 0xffff0000, v150
	v_lshlrev_b32_e32 v202, 16, v151
	v_and_b32_e32 v203, 0xffff0000, v151
	v_fmac_f32_e32 v236, v200, v200
	v_fmac_f32_e32 v237, v201, v201
	v_fmac_f32_e32 v236, v202, v202
	v_fmac_f32_e32 v237, v203, v203
	v_lshlrev_b32_e32 v200, 16, v152
	v_and_b32_e32 v201, 0xffff0000, v152
	v_lshlrev_b32_e32 v202, 16, v153
	v_and_b32_e32 v203, 0xffff0000, v153
	v_fmac_f32_e32 v236, v200, v200
	v_fmac_f32_e32 v237, v201, v201
	v_fmac_f32_e32 v236, v202, v202
	v_fmac_f32_e32 v237, v203, v203
	v_lshlrev_b32_e32 v200, 16, v154
	v_and_b32_e32 v201, 0xffff0000, v154
	v_lshlrev_b32_e32 v202, 16, v155
	v_and_b32_e32 v203, 0xffff0000, v155
	v_fmac_f32_e32 v236, v200, v200
	v_fmac_f32_e32 v237, v201, v201
	v_fmac_f32_e32 v236, v202, v202
	v_fmac_f32_e32 v237, v203, v203
	v_lshlrev_b32_e32 v200, 16, v156
	v_and_b32_e32 v201, 0xffff0000, v156
	v_lshlrev_b32_e32 v202, 16, v157
	v_and_b32_e32 v203, 0xffff0000, v157
	v_fmac_f32_e32 v236, v200, v200
	v_fmac_f32_e32 v237, v201, v201
	v_fmac_f32_e32 v236, v202, v202
	v_fmac_f32_e32 v237, v203, v203
	v_add_f32_e32 v236, v236, v237
	v_lshlrev_b32_e32 v200, 16, v184
	v_and_b32_e32 v201, 0xffff0000, v184
	v_lshlrev_b32_e32 v202, 16, v185
	v_and_b32_e32 v203, 0xffff0000, v185
	v_mul_f32_e32 v238, v200, v200
	v_mul_f32_e32 v239, v201, v201
	v_fmac_f32_e32 v238, v202, v202
	v_fmac_f32_e32 v239, v203, v203
	v_lshlrev_b32_e32 v200, 16, v186
	v_and_b32_e32 v201, 0xffff0000, v186
	v_lshlrev_b32_e32 v202, 16, v187
	v_and_b32_e32 v203, 0xffff0000, v187
	v_fmac_f32_e32 v238, v200, v200
	v_fmac_f32_e32 v239, v201, v201
	v_fmac_f32_e32 v238, v202, v202
	v_fmac_f32_e32 v239, v203, v203
	v_lshlrev_b32_e32 v200, 16, v188
	v_and_b32_e32 v201, 0xffff0000, v188
	v_lshlrev_b32_e32 v202, 16, v189
	v_and_b32_e32 v203, 0xffff0000, v189
	v_fmac_f32_e32 v238, v200, v200
	v_fmac_f32_e32 v239, v201, v201
	v_fmac_f32_e32 v238, v202, v202
	v_fmac_f32_e32 v239, v203, v203
	v_lshlrev_b32_e32 v200, 16, v190
	v_and_b32_e32 v201, 0xffff0000, v190
	v_lshlrev_b32_e32 v202, 16, v191
	v_and_b32_e32 v203, 0xffff0000, v191
	v_fmac_f32_e32 v238, v200, v200
	v_fmac_f32_e32 v239, v201, v201
	v_fmac_f32_e32 v238, v202, v202
	v_fmac_f32_e32 v239, v203, v203
	v_lshlrev_b32_e32 v200, 16, v192
	v_and_b32_e32 v201, 0xffff0000, v192
	v_lshlrev_b32_e32 v202, 16, v193
	v_and_b32_e32 v203, 0xffff0000, v193
	v_fmac_f32_e32 v238, v200, v200
	v_fmac_f32_e32 v239, v201, v201
	v_fmac_f32_e32 v238, v202, v202
	v_fmac_f32_e32 v239, v203, v203
	v_lshlrev_b32_e32 v200, 16, v194
	v_and_b32_e32 v201, 0xffff0000, v194
	v_lshlrev_b32_e32 v202, 16, v195
	v_and_b32_e32 v203, 0xffff0000, v195
	v_fmac_f32_e32 v238, v200, v200
	v_fmac_f32_e32 v239, v201, v201
	v_fmac_f32_e32 v238, v202, v202
	v_fmac_f32_e32 v239, v203, v203
	v_lshlrev_b32_e32 v200, 16, v196
	v_and_b32_e32 v201, 0xffff0000, v196
	v_lshlrev_b32_e32 v202, 16, v197
	v_and_b32_e32 v203, 0xffff0000, v197
	v_fmac_f32_e32 v238, v200, v200
	v_fmac_f32_e32 v239, v201, v201
	v_fmac_f32_e32 v238, v202, v202
	v_fmac_f32_e32 v239, v203, v203
	v_lshlrev_b32_e32 v200, 16, v198
	v_and_b32_e32 v201, 0xffff0000, v198
	v_lshlrev_b32_e32 v202, 16, v199
	v_and_b32_e32 v203, 0xffff0000, v199
	v_fmac_f32_e32 v238, v200, v200
	v_fmac_f32_e32 v239, v201, v201
	v_fmac_f32_e32 v238, v202, v202
	v_fmac_f32_e32 v239, v203, v203
	v_add_f32_e32 v238, v238, v239
	ds_bpermute_b32 v244, v230, v236
	ds_bpermute_b32 v245, v230, v238
	s_waitcnt lgkmcnt(1)
	v_add_f32_e32 v236, v236, v244
	s_waitcnt lgkmcnt(0)
	v_add_f32_e32 v238, v238, v245
	ds_bpermute_b32 v244, v231, v236
	ds_bpermute_b32 v245, v231, v238
	s_waitcnt lgkmcnt(1)
	v_add_f32_e32 v236, v236, v244
	s_waitcnt lgkmcnt(0)
	v_add_f32_e32 v238, v238, v245
	ds_bpermute_b32 v244, v232, v236
	ds_bpermute_b32 v245, v232, v238
	s_waitcnt lgkmcnt(1)
	v_add_f32_e32 v236, v236, v244
	s_waitcnt lgkmcnt(0)
	v_add_f32_e32 v238, v238, v245
	ds_bpermute_b32 v244, v233, v236
	ds_bpermute_b32 v245, v233, v238
	s_waitcnt lgkmcnt(1)
	v_add_f32_e32 v236, v236, v244
	s_waitcnt lgkmcnt(0)
	v_add_f32_e32 v238, v238, v245
	ds_bpermute_b32 v244, v234, v236
	ds_bpermute_b32 v245, v234, v238
	s_waitcnt lgkmcnt(1)
	v_add_f32_e32 v236, v236, v244
	s_waitcnt lgkmcnt(0)
	v_add_f32_e32 v238, v238, v245
	ds_bpermute_b32 v244, v235, v236
	ds_bpermute_b32 v245, v235, v238
	s_waitcnt lgkmcnt(1)
	v_add_f32_e32 v236, v236, v244
	s_waitcnt lgkmcnt(0)
; DI void post_phase(const P& p, int l, unsigned char* smem, int t0, int t1, int bstart, int bstride) {
;     ...
;         const float rstd = rsqrtf(ss * (1.f / 2048.f) + 1e-6f);
;         const float* md = mod + (size_t)(l * 5 + mr) * 6144;
;         float ss2 = 0.f;
; #pragma unroll
;         for (int i = 0; i < 8; ++i) {
;             const int j = i * 256 + lane * 4;
;             const f32x4 hv = __builtin_nontemporal_load((const f32x4*)(h + j)), gt = *(const f32x4*)(md + 4096 + j), nw = *(const f32x4*)(p.norm_post + l * DM + j);
; #pragma unroll
;             for (int e = 0; e < 4; ++e) { y[i][e] = hv[e] + gt[e] * (y[i][e] * rstd * nw[e]); ss2 += y[i][e] * y[i][e]; }
;             __builtin_nontemporal_store(y[i], (f32x4*)(hdst + j));
	v_add_f32_e32 v238, v238, v245
	v_mov_b32_e32 v244, 0x358637bd
	v_fmamk_f32 v236, v236, 0x3a000000, v244
	v_fmamk_f32 v238, v238, 0x3a000000, v244
	v_rsq_f32_e32 v246, v236
	v_rsq_f32_e32 v247, v238
	s_nop 0
	v_lshlrev_b32_e32 v200, 16, v142
	v_and_b32_e32 v201, 0xffff0000, v142
	v_lshlrev_b32_e32 v202, 16, v143
	v_and_b32_e32 v203, 0xffff0000, v143
	v_mul_f32_e32 v200, v246, v200
	v_mul_f32_e32 v201, v246, v201
	v_mul_f32_e32 v202, v246, v202
	v_mul_f32_e32 v203, v246, v203
	s_waitcnt vmcnt(22)
	v_mul_f32_e32 v200, v96, v200
	v_mul_f32_e32 v201, v97, v201
	v_mul_f32_e32 v202, v98, v202
	v_mul_f32_e32 v203, v99, v203
	v_fma_f32 v0, v64, v200, v0
	v_fma_f32 v1, v65, v201, v1
	v_fma_f32 v2, v66, v202, v2
	v_fma_f32 v3, v67, v203, v3
	v_mul_f32_e32 v240, v0, v0
	v_mul_f32_e32 v241, v1, v1
	v_fmac_f32_e32 v240, v2, v2
	v_fmac_f32_e32 v241, v3, v3
	global_store_dwordx4 v224, v[0:3], s[44:45] offset:0 nt
	v_lshlrev_b32_e32 v200, 16, v144
	v_and_b32_e32 v201, 0xffff0000, v144
	v_lshlrev_b32_e32 v202, 16, v145
	v_and_b32_e32 v203, 0xffff0000, v145
	v_mul_f32_e32 v200, v246, v200
	v_mul_f32_e32 v201, v246, v201
	v_mul_f32_e32 v202, v246, v202
	v_mul_f32_e32 v203, v246, v203
	s_waitcnt vmcnt(20)
	v_mul_f32_e32 v200, v100, v200
	v_mul_f32_e32 v201, v101, v201
	v_mul_f32_e32 v202, v102, v202
	v_mul_f32_e32 v203, v103, v203
	v_fma_f32 v4, v68, v200, v4
	v_fma_f32 v5, v69, v201, v5
	v_fma_f32 v6, v70, v202, v6
	v_fma_f32 v7, v71, v203, v7
	v_fmac_f32_e32 v240, v4, v4
	v_fmac_f32_e32 v241, v5, v5
	v_fmac_f32_e32 v240, v6, v6
	v_fmac_f32_e32 v241, v7, v7
	global_store_dwordx4 v224, v[4:7], s[44:45] offset:1024 nt
	v_lshlrev_b32_e32 v200, 16, v146
	v_and_b32_e32 v201, 0xffff0000, v146
	v_lshlrev_b32_e32 v202, 16, v147
	v_and_b32_e32 v203, 0xffff0000, v147
	v_mul_f32_e32 v200, v246, v200
	v_mul_f32_e32 v201, v246, v201
	v_mul_f32_e32 v202, v246, v202
	v_mul_f32_e32 v203, v246, v203
	s_waitcnt vmcnt(18)
	v_mul_f32_e32 v200, v104, v200
	v_mul_f32_e32 v201, v105, v201
	v_mul_f32_e32 v202, v106, v202
	v_mul_f32_e32 v203, v107, v203
	v_fma_f32 v8, v72, v200, v8
	v_fma_f32 v9, v73, v201, v9
	v_fma_f32 v10, v74, v202, v10
	v_fma_f32 v11, v75, v203, v11
	v_fmac_f32_e32 v240, v8, v8
	v_fmac_f32_e32 v241, v9, v9
	v_fmac_f32_e32 v240, v10, v10
	v_fmac_f32_e32 v241, v11, v11
	global_store_dwordx4 v224, v[8:11], s[44:45] offset:2048 nt
	v_lshlrev_b32_e32 v200, 16, v148
	v_and_b32_e32 v201, 0xffff0000, v148
	v_lshlrev_b32_e32 v202, 16, v149
	v_and_b32_e32 v203, 0xffff0000, v149
	v_mul_f32_e32 v200, v246, v200
	v_mul_f32_e32 v201, v246, v201
	v_mul_f32_e32 v202, v246, v202
	v_mul_f32_e32 v203, v246, v203
	s_waitcnt vmcnt(16)
	v_mul_f32_e32 v200, v108, v200
	v_mul_f32_e32 v201, v109, v201
	v_mul_f32_e32 v202, v110, v202
	v_mul_f32_e32 v203, v111, v203
	v_fma_f32 v12, v76, v200, v12
	v_fma_f32 v13, v77, v201, v13
	v_fma_f32 v14, v78, v202, v14
	v_fma_f32 v15, v79, v203, v15
	v_fmac_f32_e32 v240, v12, v12
	v_fmac_f32_e32 v241, v13, v13
	v_fmac_f32_e32 v240, v14, v14
	v_fmac_f32_e32 v241, v15, v15
	global_store_dwordx4 v224, v[12:15], s[44:45] offset:3072 nt
	v_lshlrev_b32_e32 v200, 16, v150
	v_and_b32_e32 v201, 0xffff0000, v150
	v_lshlrev_b32_e32 v202, 16, v151
	v_and_b32_e32 v203, 0xffff0000, v151
	v_mul_f32_e32 v200, v246, v200
	v_mul_f32_e32 v201, v246, v201
	v_mul_f32_e32 v202, v246, v202
	v_mul_f32_e32 v203, v246, v203
	s_waitcnt vmcnt(14)
	v_mul_f32_e32 v200, v112, v200
	v_mul_f32_e32 v201, v113, v201
	v_mul_f32_e32 v202, v114, v202
	v_mul_f32_e32 v203, v115, v203
	v_fma_f32 v16, v80, v200, v16
	v_fma_f32 v17, v81, v201, v17
	v_fma_f32 v18, v82, v202, v18
	v_fma_f32 v19, v83, v203, v19
	v_fmac_f32_e32 v240, v16, v16
	v_fmac_f32_e32 v241, v17, v17
	v_fmac_f32_e32 v240, v18, v18
	v_fmac_f32_e32 v241, v19, v19
	global_store_dwordx4 v225, v[16:19], s[44:45] offset:0 nt
	v_lshlrev_b32_e32 v200, 16, v152
	v_and_b32_e32 v201, 0xffff0000, v152
	v_lshlrev_b32_e32 v202, 16, v153
	v_and_b32_e32 v203, 0xffff0000, v153
	v_mul_f32_e32 v200, v246, v200
	v_mul_f32_e32 v201, v246, v201
	v_mul_f32_e32 v202, v246, v202
	v_mul_f32_e32 v203, v246, v203
	s_waitcnt vmcnt(12)
	v_mul_f32_e32 v200, v116, v200
	v_mul_f32_e32 v201, v117, v201
	v_mul_f32_e32 v202, v118, v202
	v_mul_f32_e32 v203, v119, v203
	v_fma_f32 v20, v84, v200, v20
	v_fma_f32 v21, v85, v201, v21
	v_fma_f32 v22, v86, v202, v22
	v_fma_f32 v23, v87, v203, v23
	v_fmac_f32_e32 v240, v20, v20
	v_fmac_f32_e32 v241, v21, v21
	v_fmac_f32_e32 v240, v22, v22
	v_fmac_f32_e32 v241, v23, v23
	global_store_dwordx4 v225, v[20:23], s[44:45] offset:1024 nt
	v_lshlrev_b32_e32 v200, 16, v154
	v_and_b32_e32 v201, 0xffff0000, v154
	v_lshlrev_b32_e32 v202, 16, v155
	v_and_b32_e32 v203, 0xffff0000, v155
	v_mul_f32_e32 v200, v246, v200
	v_mul_f32_e32 v201, v246, v201
	v_mul_f32_e32 v202, v246, v202
	v_mul_f32_e32 v203, v246, v203
	s_waitcnt vmcnt(10)
	v_mul_f32_e32 v200, v120, v200
	v_mul_f32_e32 v201, v121, v201
	v_mul_f32_e32 v202, v122, v202
	v_mul_f32_e32 v203, v123, v203
	v_fma_f32 v24, v88, v200, v24
	v_fma_f32 v25, v89, v201, v25
	v_fma_f32 v26, v90, v202, v26
	v_fma_f32 v27, v91, v203, v27
	v_fmac_f32_e32 v240, v24, v24
	v_fmac_f32_e32 v241, v25, v25
	v_fmac_f32_e32 v240, v26, v26
	v_fmac_f32_e32 v241, v27, v27
	global_store_dwordx4 v225, v[24:27], s[44:45] offset:2048 nt
	v_lshlrev_b32_e32 v200, 16, v156
	v_and_b32_e32 v201, 0xffff0000, v156
	v_lshlrev_b32_e32 v202, 16, v157
	v_and_b32_e32 v203, 0xffff0000, v157
	v_mul_f32_e32 v200, v246, v200
	v_mul_f32_e32 v201, v246, v201
	v_mul_f32_e32 v202, v246, v202
	v_mul_f32_e32 v203, v246, v203
	s_waitcnt vmcnt(8)
; DI void post_phase(const P& p, int l, unsigned char* smem, int t0, int t1, int bstart, int bstride) {
;     ...
;         for (int i = 0; i < 8; ++i) {
;             const int j = i * 256 + lane * 4;
;             const f32x4 hv = __builtin_nontemporal_load((const f32x4*)(h + j)), gt = *(const f32x4*)(md + 4096 + j), nw = *(const f32x4*)(p.norm_post + l * DM + j);
; #pragma unroll
;             for (int e = 0; e < 4; ++e) { y[i][e] = hv[e] + gt[e] * (y[i][e] * rstd * nw[e]); ss2 += y[i][e] * y[i][e]; }
;             __builtin_nontemporal_store(y[i], (f32x4*)(hdst + j));
	v_mul_f32_e32 v200, v124, v200
	v_mul_f32_e32 v201, v125, v201
	v_mul_f32_e32 v202, v126, v202
	v_mul_f32_e32 v203, v127, v203
	v_fma_f32 v28, v92, v200, v28
	v_fma_f32 v29, v93, v201, v29
	v_fma_f32 v30, v94, v202, v30
	v_fma_f32 v31, v95, v203, v31
	v_fmac_f32_e32 v240, v28, v28
	v_fmac_f32_e32 v241, v29, v29
	v_fmac_f32_e32 v240, v30, v30
	v_fmac_f32_e32 v241, v31, v31
	global_store_dwordx4 v225, v[28:31], s[44:45] offset:3072 nt
	v_add_f32_e32 v240, v240, v241
	v_lshlrev_b32_e32 v200, 16, v184
	v_and_b32_e32 v201, 0xffff0000, v184
	v_lshlrev_b32_e32 v202, 16, v185
	v_and_b32_e32 v203, 0xffff0000, v185
	v_mul_f32_e32 v200, v247, v200
	v_mul_f32_e32 v201, v247, v201
	v_mul_f32_e32 v202, v247, v202
	v_mul_f32_e32 v203, v247, v203
	s_waitcnt vmcnt(7)
	v_mul_f32_e32 v200, v96, v200
	v_mul_f32_e32 v201, v97, v201
	v_mul_f32_e32 v202, v98, v202
	v_mul_f32_e32 v203, v99, v203
	v_fma_f32 v32, v64, v200, v32
	v_fma_f32 v33, v65, v201, v33
	v_fma_f32 v34, v66, v202, v34
	v_fma_f32 v35, v67, v203, v35
	v_mul_f32_e32 v242, v32, v32
	v_mul_f32_e32 v243, v33, v33
	v_fmac_f32_e32 v242, v34, v34
	v_fmac_f32_e32 v243, v35, v35
	global_store_dwordx4 v226, v[32:35], s[44:45] offset:0 nt
	v_lshlrev_b32_e32 v200, 16, v186
	v_and_b32_e32 v201, 0xffff0000, v186
	v_lshlrev_b32_e32 v202, 16, v187
	v_and_b32_e32 v203, 0xffff0000, v187
	v_mul_f32_e32 v200, v247, v200
	v_mul_f32_e32 v201, v247, v201
	v_mul_f32_e32 v202, v247, v202
	v_mul_f32_e32 v203, v247, v203
	s_waitcnt vmcnt(6)
	v_mul_f32_e32 v200, v100, v200
	v_mul_f32_e32 v201, v101, v201
	v_mul_f32_e32 v202, v102, v202
	v_mul_f32_e32 v203, v103, v203
	v_fma_f32 v36, v68, v200, v36
	v_fma_f32 v37, v69, v201, v37
	v_fma_f32 v38, v70, v202, v38
	v_fma_f32 v39, v71, v203, v39
	v_fmac_f32_e32 v242, v36, v36
	v_fmac_f32_e32 v243, v37, v37
	v_fmac_f32_e32 v242, v38, v38
	v_fmac_f32_e32 v243, v39, v39
	global_store_dwordx4 v226, v[36:39], s[44:45] offset:1024 nt
	v_lshlrev_b32_e32 v200, 16, v188
	v_and_b32_e32 v201, 0xffff0000, v188
	v_lshlrev_b32_e32 v202, 16, v189
	v_and_b32_e32 v203, 0xffff0000, v189
	v_mul_f32_e32 v200, v247, v200
	v_mul_f32_e32 v201, v247, v201
	v_mul_f32_e32 v202, v247, v202
	v_mul_f32_e32 v203, v247, v203
	s_waitcnt vmcnt(5)
	v_mul_f32_e32 v200, v104, v200
	v_mul_f32_e32 v201, v105, v201
	v_mul_f32_e32 v202, v106, v202
	v_mul_f32_e32 v203, v107, v203
	v_fma_f32 v40, v72, v200, v40
	v_fma_f32 v41, v73, v201, v41
	v_fma_f32 v42, v74, v202, v42
	v_fma_f32 v43, v75, v203, v43
	v_fmac_f32_e32 v242, v40, v40
	v_fmac_f32_e32 v243, v41, v41
	v_fmac_f32_e32 v242, v42, v42
	v_fmac_f32_e32 v243, v43, v43
	global_store_dwordx4 v226, v[40:43], s[44:45] offset:2048 nt
	v_lshlrev_b32_e32 v200, 16, v190
	v_and_b32_e32 v201, 0xffff0000, v190
	v_lshlrev_b32_e32 v202, 16, v191
	v_and_b32_e32 v203, 0xffff0000, v191
	v_mul_f32_e32 v200, v247, v200
	v_mul_f32_e32 v201, v247, v201
	v_mul_f32_e32 v202, v247, v202
	v_mul_f32_e32 v203, v247, v203
	s_waitcnt vmcnt(4)
	v_mul_f32_e32 v200, v108, v200
	v_mul_f32_e32 v201, v109, v201
	v_mul_f32_e32 v202, v110, v202
	v_mul_f32_e32 v203, v111, v203
	v_fma_f32 v44, v76, v200, v44
	v_fma_f32 v45, v77, v201, v45
	v_fma_f32 v46, v78, v202, v46
	v_fma_f32 v47, v79, v203, v47
	v_fmac_f32_e32 v242, v44, v44
	v_fmac_f32_e32 v243, v45, v45
	v_fmac_f32_e32 v242, v46, v46
	v_fmac_f32_e32 v243, v47, v47
	global_store_dwordx4 v226, v[44:47], s[44:45] offset:3072 nt
	v_lshlrev_b32_e32 v200, 16, v192
	v_and_b32_e32 v201, 0xffff0000, v192
	v_lshlrev_b32_e32 v202, 16, v193
	v_and_b32_e32 v203, 0xffff0000, v193
	v_mul_f32_e32 v200, v247, v200
	v_mul_f32_e32 v201, v247, v201
	v_mul_f32_e32 v202, v247, v202
	v_mul_f32_e32 v203, v247, v203
	s_waitcnt vmcnt(3)
	v_mul_f32_e32 v200, v112, v200
	v_mul_f32_e32 v201, v113, v201
	v_mul_f32_e32 v202, v114, v202
	v_mul_f32_e32 v203, v115, v203
	v_fma_f32 v48, v80, v200, v48
	v_fma_f32 v49, v81, v201, v49
	v_fma_f32 v50, v82, v202, v50
	v_fma_f32 v51, v83, v203, v51
	v_fmac_f32_e32 v242, v48, v48
	v_fmac_f32_e32 v243, v49, v49
	v_fmac_f32_e32 v242, v50, v50
	v_fmac_f32_e32 v243, v51, v51
	global_store_dwordx4 v227, v[48:51], s[44:45] offset:0 nt
	v_lshlrev_b32_e32 v200, 16, v194
	v_and_b32_e32 v201, 0xffff0000, v194
	v_lshlrev_b32_e32 v202, 16, v195
	v_and_b32_e32 v203, 0xffff0000, v195
	v_mul_f32_e32 v200, v247, v200
	v_mul_f32_e32 v201, v247, v201
	v_mul_f32_e32 v202, v247, v202
	v_mul_f32_e32 v203, v247, v203
	s_waitcnt vmcnt(2)
	v_mul_f32_e32 v200, v116, v200
	v_mul_f32_e32 v201, v117, v201
	v_mul_f32_e32 v202, v118, v202
	v_mul_f32_e32 v203, v119, v203
	v_fma_f32 v52, v84, v200, v52
	v_fma_f32 v53, v85, v201, v53
	v_fma_f32 v54, v86, v202, v54
	v_fma_f32 v55, v87, v203, v55
	v_fmac_f32_e32 v242, v52, v52
	v_fmac_f32_e32 v243, v53, v53
	v_fmac_f32_e32 v242, v54, v54
	v_fmac_f32_e32 v243, v55, v55
	global_store_dwordx4 v227, v[52:55], s[44:45] offset:1024 nt
	v_lshlrev_b32_e32 v200, 16, v196
	v_and_b32_e32 v201, 0xffff0000, v196
	v_lshlrev_b32_e32 v202, 16, v197
	v_and_b32_e32 v203, 0xffff0000, v197
	v_mul_f32_e32 v200, v247, v200
	v_mul_f32_e32 v201, v247, v201
	v_mul_f32_e32 v202, v247, v202
	v_mul_f32_e32 v203, v247, v203
	s_waitcnt vmcnt(1)
	v_mul_f32_e32 v200, v120, v200
	v_mul_f32_e32 v201, v121, v201
	v_mul_f32_e32 v202, v122, v202
	v_mul_f32_e32 v203, v123, v203
	v_fma_f32 v56, v88, v200, v56
	v_fma_f32 v57, v89, v201, v57
	v_fma_f32 v58, v90, v202, v58
	v_fma_f32 v59, v91, v203, v59
	v_fmac_f32_e32 v242, v56, v56
	v_fmac_f32_e32 v243, v57, v57
	v_fmac_f32_e32 v242, v58, v58
	v_fmac_f32_e32 v243, v59, v59
	global_store_dwordx4 v227, v[56:59], s[44:45] offset:2048 nt
	v_lshlrev_b32_e32 v200, 16, v198
	v_and_b32_e32 v201, 0xffff0000, v198
	v_lshlrev_b32_e32 v202, 16, v199
	v_and_b32_e32 v203, 0xffff0000, v199
	v_mul_f32_e32 v200, v247, v200
	v_mul_f32_e32 v201, v247, v201
	v_mul_f32_e32 v202, v247, v202
	v_mul_f32_e32 v203, v247, v203
	s_waitcnt vmcnt(0)
; DI void post_phase(const P& p, int l, unsigned char* smem, int t0, int t1, int bstart, int bstride) {
;     ...
;         for (int i = 0; i < 8; ++i) {
;             const int j = i * 256 + lane * 4;
;             const f32x4 hv = __builtin_nontemporal_load((const f32x4*)(h + j)), gt = *(const f32x4*)(md + 4096 + j), nw = *(const f32x4*)(p.norm_post + l * DM + j);
; #pragma unroll
;             for (int e = 0; e < 4; ++e) { y[i][e] = hv[e] + gt[e] * (y[i][e] * rstd * nw[e]); ss2 += y[i][e] * y[i][e]; }
;             __builtin_nontemporal_store(y[i], (f32x4*)(hdst + j));
;         }
;         if (l == 0) {
;             ss2 = wave_sum(ss2);
;             const float rstd2 = rsqrtf(ss2 * (1.f / 2048.f) + 1e-6f);
;             const float* md1 = mod + (size_t)(5 + mr) * 6144;
; #pragma unroll
;             for (int i = 0; i < 8; ++i) {
;                 const int j = i * 256 + lane * 4;
;                 const f32x4 gw = *(const f32x4*)(p.norm_pre + DM + j), sh = *(const f32x4*)(md1 + j), scl = *(const f32x4*)(md1 + 2048 + j);
;                 float o[4];
; #pragma unroll
;                 for (int e = 0; e < 4; ++e) o[e] = y[i][e] * rstd2 * gw[e] * (1.f + scl[e]) + sh[e];
;                 u32x2 w; w.x = pk2(o[0], o[1]); w.y = pk2(o[2], o[3]);
;                 *(u32x2*)(nb + (size_t)row * DM + j) = w;
;             }
	v_mul_f32_e32 v200, v124, v200
	v_mul_f32_e32 v201, v125, v201
	v_mul_f32_e32 v202, v126, v202
	v_mul_f32_e32 v203, v127, v203
	v_fma_f32 v60, v92, v200, v60
	v_fma_f32 v61, v93, v201, v61
	v_fma_f32 v62, v94, v202, v62
	v_fma_f32 v63, v95, v203, v63
	v_fmac_f32_e32 v242, v60, v60
	v_fmac_f32_e32 v243, v61, v61
	v_fmac_f32_e32 v242, v62, v62
	v_fmac_f32_e32 v243, v63, v63
	global_store_dwordx4 v227, v[60:63], s[44:45] offset:3072 nt
	v_add_f32_e32 v242, v242, v243
	global_load_dwordx4 v[64:67], v224, s[4:5] offset:0
	global_load_dwordx4 v[96:99], v224, s[48:49] offset:0
	global_load_dwordx4 v[142:145], v226, s[48:49] offset:0
	global_load_dwordx4 v[68:71], v224, s[4:5] offset:1024
	global_load_dwordx4 v[100:103], v224, s[48:49] offset:1024
	global_load_dwordx4 v[146:149], v226, s[48:49] offset:1024
	global_load_dwordx4 v[72:75], v224, s[4:5] offset:2048
	global_load_dwordx4 v[104:107], v224, s[48:49] offset:2048
	global_load_dwordx4 v[150:153], v226, s[48:49] offset:2048
	global_load_dwordx4 v[76:79], v224, s[4:5] offset:3072
	global_load_dwordx4 v[108:111], v224, s[48:49] offset:3072
	global_load_dwordx4 v[154:157], v226, s[48:49] offset:3072
	global_load_dwordx4 v[80:83], v225, s[4:5] offset:0
	global_load_dwordx4 v[112:115], v225, s[48:49] offset:0
	global_load_dwordx4 v[184:187], v227, s[48:49] offset:0
	global_load_dwordx4 v[84:87], v225, s[4:5] offset:1024
	global_load_dwordx4 v[116:119], v225, s[48:49] offset:1024
	global_load_dwordx4 v[188:191], v227, s[48:49] offset:1024
	global_load_dwordx4 v[88:91], v225, s[4:5] offset:2048
	global_load_dwordx4 v[120:123], v225, s[48:49] offset:2048
	global_load_dwordx4 v[192:195], v227, s[48:49] offset:2048
	global_load_dwordx4 v[92:95], v225, s[4:5] offset:3072
	global_load_dwordx4 v[124:127], v225, s[48:49] offset:3072
	global_load_dwordx4 v[196:199], v227, s[48:49] offset:3072
	ds_bpermute_b32 v244, v230, v240
	ds_bpermute_b32 v245, v230, v242
	s_waitcnt lgkmcnt(1)
	v_add_f32_e32 v240, v240, v244
	s_waitcnt lgkmcnt(0)
	v_add_f32_e32 v242, v242, v245
	ds_bpermute_b32 v244, v231, v240
	ds_bpermute_b32 v245, v231, v242
	s_waitcnt lgkmcnt(1)
	v_add_f32_e32 v240, v240, v244
	s_waitcnt lgkmcnt(0)
	v_add_f32_e32 v242, v242, v245
	ds_bpermute_b32 v244, v232, v240
	ds_bpermute_b32 v245, v232, v242
	s_waitcnt lgkmcnt(1)
	v_add_f32_e32 v240, v240, v244
	s_waitcnt lgkmcnt(0)
	v_add_f32_e32 v242, v242, v245
	ds_bpermute_b32 v244, v233, v240
	ds_bpermute_b32 v245, v233, v242
	s_waitcnt lgkmcnt(1)
	v_add_f32_e32 v240, v240, v244
	s_waitcnt lgkmcnt(0)
	v_add_f32_e32 v242, v242, v245
	ds_bpermute_b32 v244, v234, v240
	ds_bpermute_b32 v245, v234, v242
	s_waitcnt lgkmcnt(1)
	v_add_f32_e32 v240, v240, v244
	s_waitcnt lgkmcnt(0)
	v_add_f32_e32 v242, v242, v245
	ds_bpermute_b32 v244, v235, v240
	ds_bpermute_b32 v245, v235, v242
	s_waitcnt lgkmcnt(1)
	v_add_f32_e32 v240, v240, v244
	s_waitcnt lgkmcnt(0)
	v_add_f32_e32 v242, v242, v245
	v_mov_b32_e32 v244, 0x358637bd
	v_fmamk_f32 v240, v240, 0x3a000000, v244
	v_fmamk_f32 v242, v242, 0x3a000000, v244
	v_rsq_f32_e32 v246, v240
	v_rsq_f32_e32 v247, v242
	s_nop 0
	v_mul_f32_e32 v200, v0, v246
	v_mul_f32_e32 v201, v1, v246
	v_mul_f32_e32 v202, v2, v246
	v_mul_f32_e32 v203, v3, v246
	s_waitcnt vmcnt(21)
	v_mul_f32_e32 v200, v200, v64
	v_mul_f32_e32 v201, v201, v65
	v_mul_f32_e32 v202, v202, v66
	v_mul_f32_e32 v203, v203, v67
	v_add_f32_e32 v204, 1.0, v142
	v_add_f32_e32 v205, 1.0, v143
	v_add_f32_e32 v206, 1.0, v144
	v_add_f32_e32 v207, 1.0, v145
	v_fma_f32 v200, v200, v204, v96
	v_fma_f32 v201, v201, v205, v97
	v_fma_f32 v202, v202, v206, v98
	v_fma_f32 v203, v203, v207, v99
	v_cvt_pk_bf16_f32 v208, v200, v201
	v_cvt_pk_bf16_f32 v209, v202, v203
	global_store_dwordx2 v228, v[208:209], s[30:31] offset:0
	v_mul_f32_e32 v200, v4, v246
	v_mul_f32_e32 v201, v5, v246
	v_mul_f32_e32 v202, v6, v246
	v_mul_f32_e32 v203, v7, v246
	s_waitcnt vmcnt(18)
	v_mul_f32_e32 v200, v200, v68
	v_mul_f32_e32 v201, v201, v69
	v_mul_f32_e32 v202, v202, v70
	v_mul_f32_e32 v203, v203, v71
	v_add_f32_e32 v204, 1.0, v146
	v_add_f32_e32 v205, 1.0, v147
	v_add_f32_e32 v206, 1.0, v148
	v_add_f32_e32 v207, 1.0, v149
	v_fma_f32 v200, v200, v204, v100
	v_fma_f32 v201, v201, v205, v101
	v_fma_f32 v202, v202, v206, v102
	v_fma_f32 v203, v203, v207, v103
	v_cvt_pk_bf16_f32 v210, v200, v201
	v_cvt_pk_bf16_f32 v211, v202, v203
	global_store_dwordx2 v228, v[210:211], s[30:31] offset:512
	v_mul_f32_e32 v200, v8, v246
	v_mul_f32_e32 v201, v9, v246
	v_mul_f32_e32 v202, v10, v246
	v_mul_f32_e32 v203, v11, v246
	s_waitcnt vmcnt(15)
	v_mul_f32_e32 v200, v200, v72
	v_mul_f32_e32 v201, v201, v73
	v_mul_f32_e32 v202, v202, v74
	v_mul_f32_e32 v203, v203, v75
	v_add_f32_e32 v204, 1.0, v150
	v_add_f32_e32 v205, 1.0, v151
	v_add_f32_e32 v206, 1.0, v152
	v_add_f32_e32 v207, 1.0, v153
	v_fma_f32 v200, v200, v204, v104
	v_fma_f32 v201, v201, v205, v105
	v_fma_f32 v202, v202, v206, v106
	v_fma_f32 v203, v203, v207, v107
	v_cvt_pk_bf16_f32 v208, v200, v201
	v_cvt_pk_bf16_f32 v209, v202, v203
	global_store_dwordx2 v228, v[208:209], s[30:31] offset:1024
	v_mul_f32_e32 v200, v12, v246
	v_mul_f32_e32 v201, v13, v246
	v_mul_f32_e32 v202, v14, v246
	v_mul_f32_e32 v203, v15, v246
	s_waitcnt vmcnt(12)
	v_mul_f32_e32 v200, v200, v76
	v_mul_f32_e32 v201, v201, v77
	v_mul_f32_e32 v202, v202, v78
	v_mul_f32_e32 v203, v203, v79
	v_add_f32_e32 v204, 1.0, v154
	v_add_f32_e32 v205, 1.0, v155
	v_add_f32_e32 v206, 1.0, v156
	v_add_f32_e32 v207, 1.0, v157
	v_fma_f32 v200, v200, v204, v108
	v_fma_f32 v201, v201, v205, v109
	v_fma_f32 v202, v202, v206, v110
	v_fma_f32 v203, v203, v207, v111
	v_cvt_pk_bf16_f32 v210, v200, v201
	v_cvt_pk_bf16_f32 v211, v202, v203
	global_store_dwordx2 v228, v[210:211], s[30:31] offset:1536
	v_mul_f32_e32 v200, v16, v246
	v_mul_f32_e32 v201, v17, v246
	v_mul_f32_e32 v202, v18, v246
	v_mul_f32_e32 v203, v19, v246
	s_waitcnt vmcnt(9)
; DI void post_phase(const P& p, int l, unsigned char* smem, int t0, int t1, int bstart, int bstride) {
;     ...
;             for (int i = 0; i < 8; ++i) {
;                 const int j = i * 256 + lane * 4;
;                 const f32x4 gw = *(const f32x4*)(p.norm_pre + DM + j), sh = *(const f32x4*)(md1 + j), scl = *(const f32x4*)(md1 + 2048 + j);
;                 float o[4];
; #pragma unroll
;                 for (int e = 0; e < 4; ++e) o[e] = y[i][e] * rstd2 * gw[e] * (1.f + scl[e]) + sh[e];
;                 u32x2 w; w.x = pk2(o[0], o[1]); w.y = pk2(o[2], o[3]);
;                 *(u32x2*)(nb + (size_t)row * DM + j) = w;
;             }
	v_mul_f32_e32 v200, v200, v80
	v_mul_f32_e32 v201, v201, v81
	v_mul_f32_e32 v202, v202, v82
	v_mul_f32_e32 v203, v203, v83
	v_add_f32_e32 v204, 1.0, v184
	v_add_f32_e32 v205, 1.0, v185
	v_add_f32_e32 v206, 1.0, v186
	v_add_f32_e32 v207, 1.0, v187
	v_fma_f32 v200, v200, v204, v112
	v_fma_f32 v201, v201, v205, v113
	v_fma_f32 v202, v202, v206, v114
	v_fma_f32 v203, v203, v207, v115
	v_cvt_pk_bf16_f32 v208, v200, v201
	v_cvt_pk_bf16_f32 v209, v202, v203
	global_store_dwordx2 v228, v[208:209], s[30:31] offset:2048
	v_mul_f32_e32 v200, v20, v246
	v_mul_f32_e32 v201, v21, v246
	v_mul_f32_e32 v202, v22, v246
	v_mul_f32_e32 v203, v23, v246
	s_waitcnt vmcnt(6)
	v_mul_f32_e32 v200, v200, v84
	v_mul_f32_e32 v201, v201, v85
	v_mul_f32_e32 v202, v202, v86
	v_mul_f32_e32 v203, v203, v87
	v_add_f32_e32 v204, 1.0, v188
	v_add_f32_e32 v205, 1.0, v189
	v_add_f32_e32 v206, 1.0, v190
	v_add_f32_e32 v207, 1.0, v191
	v_fma_f32 v200, v200, v204, v116
	v_fma_f32 v201, v201, v205, v117
	v_fma_f32 v202, v202, v206, v118
	v_fma_f32 v203, v203, v207, v119
	v_cvt_pk_bf16_f32 v210, v200, v201
	v_cvt_pk_bf16_f32 v211, v202, v203
	global_store_dwordx2 v228, v[210:211], s[30:31] offset:2560
	v_mul_f32_e32 v200, v24, v246
	v_mul_f32_e32 v201, v25, v246
	v_mul_f32_e32 v202, v26, v246
	v_mul_f32_e32 v203, v27, v246
	s_waitcnt vmcnt(3)
	v_mul_f32_e32 v200, v200, v88
	v_mul_f32_e32 v201, v201, v89
	v_mul_f32_e32 v202, v202, v90
	v_mul_f32_e32 v203, v203, v91
	v_add_f32_e32 v204, 1.0, v192
	v_add_f32_e32 v205, 1.0, v193
	v_add_f32_e32 v206, 1.0, v194
	v_add_f32_e32 v207, 1.0, v195
	v_fma_f32 v200, v200, v204, v120
	v_fma_f32 v201, v201, v205, v121
	v_fma_f32 v202, v202, v206, v122
	v_fma_f32 v203, v203, v207, v123
	v_cvt_pk_bf16_f32 v208, v200, v201
	v_cvt_pk_bf16_f32 v209, v202, v203
	global_store_dwordx2 v228, v[208:209], s[30:31] offset:3072
	v_mul_f32_e32 v200, v28, v246
	v_mul_f32_e32 v201, v29, v246
	v_mul_f32_e32 v202, v30, v246
	v_mul_f32_e32 v203, v31, v246
	s_waitcnt vmcnt(0)
	v_mul_f32_e32 v200, v200, v92
	v_mul_f32_e32 v201, v201, v93
	v_mul_f32_e32 v202, v202, v94
	v_mul_f32_e32 v203, v203, v95
	v_add_f32_e32 v204, 1.0, v196
	v_add_f32_e32 v205, 1.0, v197
	v_add_f32_e32 v206, 1.0, v198
	v_add_f32_e32 v207, 1.0, v199
	v_fma_f32 v200, v200, v204, v124
	v_fma_f32 v201, v201, v205, v125
	v_fma_f32 v202, v202, v206, v126
	v_fma_f32 v203, v203, v207, v127
	v_cvt_pk_bf16_f32 v210, v200, v201
	v_cvt_pk_bf16_f32 v211, v202, v203
	global_store_dwordx2 v228, v[210:211], s[30:31] offset:3584
	v_mul_f32_e32 v200, v32, v247
	v_mul_f32_e32 v201, v33, v247
	v_mul_f32_e32 v202, v34, v247
	v_mul_f32_e32 v203, v35, v247
	v_mul_f32_e32 v200, v200, v64
	v_mul_f32_e32 v201, v201, v65
	v_mul_f32_e32 v202, v202, v66
	v_mul_f32_e32 v203, v203, v67
	v_add_f32_e32 v204, 1.0, v142
	v_add_f32_e32 v205, 1.0, v143
	v_add_f32_e32 v206, 1.0, v144
	v_add_f32_e32 v207, 1.0, v145
	v_fma_f32 v200, v200, v204, v96
	v_fma_f32 v201, v201, v205, v97
	v_fma_f32 v202, v202, v206, v98
	v_fma_f32 v203, v203, v207, v99
	v_cvt_pk_bf16_f32 v208, v200, v201
	v_cvt_pk_bf16_f32 v209, v202, v203
	global_store_dwordx2 v229, v[208:209], s[30:31] offset:0
	v_mul_f32_e32 v200, v36, v247
	v_mul_f32_e32 v201, v37, v247
	v_mul_f32_e32 v202, v38, v247
	v_mul_f32_e32 v203, v39, v247
	v_mul_f32_e32 v200, v200, v68
	v_mul_f32_e32 v201, v201, v69
	v_mul_f32_e32 v202, v202, v70
	v_mul_f32_e32 v203, v203, v71
	v_add_f32_e32 v204, 1.0, v146
	v_add_f32_e32 v205, 1.0, v147
	v_add_f32_e32 v206, 1.0, v148
	v_add_f32_e32 v207, 1.0, v149
	v_fma_f32 v200, v200, v204, v100
	v_fma_f32 v201, v201, v205, v101
	v_fma_f32 v202, v202, v206, v102
	v_fma_f32 v203, v203, v207, v103
	v_cvt_pk_bf16_f32 v210, v200, v201
	v_cvt_pk_bf16_f32 v211, v202, v203
	global_store_dwordx2 v229, v[210:211], s[30:31] offset:512
	v_mul_f32_e32 v200, v40, v247
	v_mul_f32_e32 v201, v41, v247
	v_mul_f32_e32 v202, v42, v247
	v_mul_f32_e32 v203, v43, v247
	v_mul_f32_e32 v200, v200, v72
	v_mul_f32_e32 v201, v201, v73
	v_mul_f32_e32 v202, v202, v74
	v_mul_f32_e32 v203, v203, v75
	v_add_f32_e32 v204, 1.0, v150
	v_add_f32_e32 v205, 1.0, v151
	v_add_f32_e32 v206, 1.0, v152
	v_add_f32_e32 v207, 1.0, v153
	v_fma_f32 v200, v200, v204, v104
	v_fma_f32 v201, v201, v205, v105
	v_fma_f32 v202, v202, v206, v106
	v_fma_f32 v203, v203, v207, v107
	v_cvt_pk_bf16_f32 v208, v200, v201
	v_cvt_pk_bf16_f32 v209, v202, v203
	global_store_dwordx2 v229, v[208:209], s[30:31] offset:1024
	v_mul_f32_e32 v200, v44, v247
	v_mul_f32_e32 v201, v45, v247
	v_mul_f32_e32 v202, v46, v247
	v_mul_f32_e32 v203, v47, v247
	v_mul_f32_e32 v200, v200, v76
	v_mul_f32_e32 v201, v201, v77
	v_mul_f32_e32 v202, v202, v78
	v_mul_f32_e32 v203, v203, v79
	v_add_f32_e32 v204, 1.0, v154
	v_add_f32_e32 v205, 1.0, v155
	v_add_f32_e32 v206, 1.0, v156
	v_add_f32_e32 v207, 1.0, v157
	v_fma_f32 v200, v200, v204, v108
	v_fma_f32 v201, v201, v205, v109
	v_fma_f32 v202, v202, v206, v110
	v_fma_f32 v203, v203, v207, v111
	v_cvt_pk_bf16_f32 v210, v200, v201
	v_cvt_pk_bf16_f32 v211, v202, v203
	global_store_dwordx2 v229, v[210:211], s[30:31] offset:1536
	v_mul_f32_e32 v200, v48, v247
	v_mul_f32_e32 v201, v49, v247
	v_mul_f32_e32 v202, v50, v247
	v_mul_f32_e32 v203, v51, v247
	v_mul_f32_e32 v200, v200, v80
	v_mul_f32_e32 v201, v201, v81
	v_mul_f32_e32 v202, v202, v82
	v_mul_f32_e32 v203, v203, v83
	v_add_f32_e32 v204, 1.0, v184
	v_add_f32_e32 v205, 1.0, v185
	v_add_f32_e32 v206, 1.0, v186
	v_add_f32_e32 v207, 1.0, v187
	v_fma_f32 v200, v200, v204, v112
	v_fma_f32 v201, v201, v205, v113
	v_fma_f32 v202, v202, v206, v114
	v_fma_f32 v203, v203, v207, v115
	v_cvt_pk_bf16_f32 v208, v200, v201
	v_cvt_pk_bf16_f32 v209, v202, v203
; DI void post_phase(const P& p, int l, unsigned char* smem, int t0, int t1, int bstart, int bstride) {
;     ...
;             for (int i = 0; i < 8; ++i) {
;                 const int j = i * 256 + lane * 4;
;                 const f32x4 gw = *(const f32x4*)(p.norm_pre + DM + j), sh = *(const f32x4*)(md1 + j), scl = *(const f32x4*)(md1 + 2048 + j);
;                 float o[4];
; #pragma unroll
;                 for (int e = 0; e < 4; ++e) o[e] = y[i][e] * rstd2 * gw[e] * (1.f + scl[e]) + sh[e];
;                 u32x2 w; w.x = pk2(o[0], o[1]); w.y = pk2(o[2], o[3]);
;                 *(u32x2*)(nb + (size_t)row * DM + j) = w;
;             }
;         }
;       }
;       if (l == 0) { asm volatile("s_waitcnt vmcnt(0)" ::: "memory"); __syncthreads(); skinny_tile(p, 1, rt * 16, (float*)smem); }
	global_store_dwordx2 v229, v[208:209], s[30:31] offset:2048
	v_mul_f32_e32 v200, v52, v247
	v_mul_f32_e32 v201, v53, v247
	v_mul_f32_e32 v202, v54, v247
	v_mul_f32_e32 v203, v55, v247
	v_mul_f32_e32 v200, v200, v84
	v_mul_f32_e32 v201, v201, v85
	v_mul_f32_e32 v202, v202, v86
	v_mul_f32_e32 v203, v203, v87
	v_add_f32_e32 v204, 1.0, v188
	v_add_f32_e32 v205, 1.0, v189
	v_add_f32_e32 v206, 1.0, v190
	v_add_f32_e32 v207, 1.0, v191
	v_fma_f32 v200, v200, v204, v116
	v_fma_f32 v201, v201, v205, v117
	v_fma_f32 v202, v202, v206, v118
	v_fma_f32 v203, v203, v207, v119
	v_cvt_pk_bf16_f32 v210, v200, v201
	v_cvt_pk_bf16_f32 v211, v202, v203
	global_store_dwordx2 v229, v[210:211], s[30:31] offset:2560
	v_mul_f32_e32 v200, v56, v247
	v_mul_f32_e32 v201, v57, v247
	v_mul_f32_e32 v202, v58, v247
	v_mul_f32_e32 v203, v59, v247
	v_mul_f32_e32 v200, v200, v88
	v_mul_f32_e32 v201, v201, v89
	v_mul_f32_e32 v202, v202, v90
	v_mul_f32_e32 v203, v203, v91
	v_add_f32_e32 v204, 1.0, v192
	v_add_f32_e32 v205, 1.0, v193
	v_add_f32_e32 v206, 1.0, v194
	v_add_f32_e32 v207, 1.0, v195
	v_fma_f32 v200, v200, v204, v120
	v_fma_f32 v201, v201, v205, v121
	v_fma_f32 v202, v202, v206, v122
	v_fma_f32 v203, v203, v207, v123
	v_cvt_pk_bf16_f32 v208, v200, v201
	v_cvt_pk_bf16_f32 v209, v202, v203
	global_store_dwordx2 v229, v[208:209], s[30:31] offset:3072
	v_mul_f32_e32 v200, v60, v247
	v_mul_f32_e32 v201, v61, v247
	v_mul_f32_e32 v202, v62, v247
	v_mul_f32_e32 v203, v63, v247
	v_mul_f32_e32 v200, v200, v92
	v_mul_f32_e32 v201, v201, v93
	v_mul_f32_e32 v202, v202, v94
	v_mul_f32_e32 v203, v203, v95
	v_add_f32_e32 v204, 1.0, v196
	v_add_f32_e32 v205, 1.0, v197
	v_add_f32_e32 v206, 1.0, v198
	v_add_f32_e32 v207, 1.0, v199
	v_fma_f32 v200, v200, v204, v124
	v_fma_f32 v201, v201, v205, v125
	v_fma_f32 v202, v202, v206, v126
	v_fma_f32 v203, v203, v207, v127
	v_cvt_pk_bf16_f32 v210, v200, v201
	v_cvt_pk_bf16_f32 v211, v202, v203
	global_store_dwordx2 v229, v[210:211], s[30:31] offset:3584
	s_lshl_b32 s36, s98, 16
	s_add_u32 s36, s36, 0x483c000
	s_add_u32 s36, s0, s36
	s_addc_u32 s37, s1, 0
	s_waitcnt vmcnt(0)
	s_barrier
; DI f32x4 mfma16(bf16x8 a, bf16x8 b, f32x4 c) { return __builtin_amdgcn_mfma_f32_16x16x32_bf16(a, b, c, 0, 0, 0); }
; DI int otid() { int t = threadIdx.x; asm volatile("" : "+v"(t)); return t; }
; DI void skinny_tile(const P& p, int l, int r0, float* red) {
;     const bf16_t* A = (const bf16_t*)(p.ws + WS_NBUF);
;     const bf16_t* Bt = (const bf16_t*)(p.ws + WS_WNT) + (size_t)l * NNAR * DM;
;     float* G = (float*)(p.ws + WS_G);
;     const int tid = otid(), w = tid >> 6, lane = tid & 63, l15 = lane & 15, g = lane >> 4;
;     f32x4 acc[3];
; #pragma unroll
;     for (int n = 0; n < 3; ++n) acc[n] = (f32x4){0.f, 0.f, 0.f, 0.f};
;     const bf16_t* ap = A + (size_t)(r0 + l15) * DM + 256 * w + 8 * g;
;     const bf16_t* bp = Bt + (size_t)l15 * DM + 256 * w + 8 * g;
; #pragma unroll
;     for (int ks = 0; ks < 8; ++ks) {
;         const bf16x8 a0 = *(const bf16x8*)(ap + 32 * ks);
; #pragma unroll
;         for (int n = 0; n < 3; ++n) acc[n] = mfma16(a0, *(const bf16x8*)(bp + (size_t)16 * n * DM + 32 * ks), acc[n]);
;     }
; #pragma unroll
;     for (int n = 0; n < 3; ++n)
; #pragma unroll
;         for (int r = 0; r < 4; ++r) red[w * 768 + (4 * g + r) * 48 + 16 * n + l15] = acc[n][r];
;     __syncthreads();
;     for (int e = tid; e < 768; e += 512) {
;         float sum = 0.f;
; #pragma unroll
;         for (int k = 0; k < 8; ++k) sum += red[k * 768 + e];
;         G[(size_t)r0 * NNAR + e] = sum;
;     }
;     __syncthreads();
	global_load_dwordx4 v[0:3], v212, s[36:37] offset:0
	global_load_dwordx4 v[32:35], v212, s[6:7] offset:0
	global_load_dwordx4 v[36:39], v213, s[6:7] offset:0
	global_load_dwordx4 v[40:43], v214, s[6:7] offset:0
	global_load_dwordx4 v[4:7], v212, s[36:37] offset:64
	global_load_dwordx4 v[44:47], v212, s[6:7] offset:64
	global_load_dwordx4 v[48:51], v213, s[6:7] offset:64
	global_load_dwordx4 v[52:55], v214, s[6:7] offset:64
	global_load_dwordx4 v[8:11], v212, s[36:37] offset:128
	global_load_dwordx4 v[56:59], v212, s[6:7] offset:128
	global_load_dwordx4 v[60:63], v213, s[6:7] offset:128
	global_load_dwordx4 v[64:67], v214, s[6:7] offset:128
	global_load_dwordx4 v[12:15], v212, s[36:37] offset:192
	global_load_dwordx4 v[68:71], v212, s[6:7] offset:192
	global_load_dwordx4 v[72:75], v213, s[6:7] offset:192
	global_load_dwordx4 v[76:79], v214, s[6:7] offset:192
	global_load_dwordx4 v[16:19], v212, s[36:37] offset:256
	global_load_dwordx4 v[80:83], v212, s[6:7] offset:256
	global_load_dwordx4 v[84:87], v213, s[6:7] offset:256
	global_load_dwordx4 v[88:91], v214, s[6:7] offset:256
	global_load_dwordx4 v[20:23], v212, s[36:37] offset:320
	global_load_dwordx4 v[92:95], v212, s[6:7] offset:320
	global_load_dwordx4 v[96:99], v213, s[6:7] offset:320
	global_load_dwordx4 v[100:103], v214, s[6:7] offset:320
	global_load_dwordx4 v[24:27], v212, s[36:37] offset:384
	global_load_dwordx4 v[104:107], v212, s[6:7] offset:384
	global_load_dwordx4 v[108:111], v213, s[6:7] offset:384
	global_load_dwordx4 v[112:115], v214, s[6:7] offset:384
	global_load_dwordx4 v[28:31], v212, s[36:37] offset:448
	global_load_dwordx4 v[116:119], v212, s[6:7] offset:448
	global_load_dwordx4 v[120:123], v213, s[6:7] offset:448
	global_load_dwordx4 v[124:127], v214, s[6:7] offset:448
	s_waitcnt vmcnt(30)
	v_mfma_f32_16x16x32_bf16 v[142:145], v[0:3], v[32:35], 0
	s_waitcnt vmcnt(29)
	v_mfma_f32_16x16x32_bf16 v[146:149], v[0:3], v[36:39], 0
	s_waitcnt vmcnt(28)
	v_mfma_f32_16x16x32_bf16 v[150:153], v[0:3], v[40:43], 0
	s_waitcnt vmcnt(26)
	v_mfma_f32_16x16x32_bf16 v[142:145], v[4:7], v[44:47], v[142:145]
	s_waitcnt vmcnt(25)
	v_mfma_f32_16x16x32_bf16 v[146:149], v[4:7], v[48:51], v[146:149]
	s_waitcnt vmcnt(24)
	v_mfma_f32_16x16x32_bf16 v[150:153], v[4:7], v[52:55], v[150:153]
	s_waitcnt vmcnt(22)
	v_mfma_f32_16x16x32_bf16 v[142:145], v[8:11], v[56:59], v[142:145]
	s_waitcnt vmcnt(21)
	v_mfma_f32_16x16x32_bf16 v[146:149], v[8:11], v[60:63], v[146:149]
	s_waitcnt vmcnt(20)
	v_mfma_f32_16x16x32_bf16 v[150:153], v[8:11], v[64:67], v[150:153]
	s_waitcnt vmcnt(18)
	v_mfma_f32_16x16x32_bf16 v[142:145], v[12:15], v[68:71], v[142:145]
	s_waitcnt vmcnt(17)
	v_mfma_f32_16x16x32_bf16 v[146:149], v[12:15], v[72:75], v[146:149]
	s_waitcnt vmcnt(16)
	v_mfma_f32_16x16x32_bf16 v[150:153], v[12:15], v[76:79], v[150:153]
	s_waitcnt vmcnt(14)
	v_mfma_f32_16x16x32_bf16 v[142:145], v[16:19], v[80:83], v[142:145]
	s_waitcnt vmcnt(13)
	v_mfma_f32_16x16x32_bf16 v[146:149], v[16:19], v[84:87], v[146:149]
	s_waitcnt vmcnt(12)
	v_mfma_f32_16x16x32_bf16 v[150:153], v[16:19], v[88:91], v[150:153]
	s_waitcnt vmcnt(10)
	v_mfma_f32_16x16x32_bf16 v[142:145], v[20:23], v[92:95], v[142:145]
	s_waitcnt vmcnt(9)
	v_mfma_f32_16x16x32_bf16 v[146:149], v[20:23], v[96:99], v[146:149]
	s_waitcnt vmcnt(8)
	v_mfma_f32_16x16x32_bf16 v[150:153], v[20:23], v[100:103], v[150:153]
	s_waitcnt vmcnt(6)
	v_mfma_f32_16x16x32_bf16 v[142:145], v[24:27], v[104:107], v[142:145]
	s_waitcnt vmcnt(5)
	v_mfma_f32_16x16x32_bf16 v[146:149], v[24:27], v[108:111], v[146:149]
	s_waitcnt vmcnt(4)
	v_mfma_f32_16x16x32_bf16 v[150:153], v[24:27], v[112:115], v[150:153]
	s_waitcnt vmcnt(2)
	v_mfma_f32_16x16x32_bf16 v[142:145], v[28:31], v[116:119], v[142:145]
	s_waitcnt vmcnt(1)
	v_mfma_f32_16x16x32_bf16 v[146:149], v[28:31], v[120:123], v[146:149]
	s_waitcnt vmcnt(0)
	v_mfma_f32_16x16x32_bf16 v[150:153], v[28:31], v[124:127], v[150:153]
	s_nop 9
	ds_write_b32 v215, v142 offset:0
	ds_write_b32 v215, v143 offset:192
	ds_write_b32 v215, v144 offset:384
	ds_write_b32 v215, v145 offset:576
	ds_write_b32 v215, v146 offset:64
	ds_write_b32 v215, v147 offset:256
	ds_write_b32 v215, v148 offset:448
	ds_write_b32 v215, v149 offset:640
	ds_write_b32 v215, v150 offset:128
	ds_write_b32 v215, v151 offset:320
	ds_write_b32 v215, v152 offset:512
	ds_write_b32 v215, v153 offset:704
	s_waitcnt lgkmcnt(0)
	s_barrier
	ds_read_b32 v184, v216 offset:0
	ds_read_b32 v185, v216 offset:3072
	ds_read_b32 v186, v216 offset:6144
	ds_read_b32 v187, v216 offset:9216
	ds_read_b32 v188, v216 offset:12288
	ds_read_b32 v189, v216 offset:15360
	ds_read_b32 v190, v216 offset:18432
	ds_read_b32 v191, v216 offset:21504
	ds_read_b32 v192, v216 offset:2048
	ds_read_b32 v193, v216 offset:5120
	ds_read_b32 v194, v216 offset:8192
	ds_read_b32 v195, v216 offset:11264
	ds_read_b32 v196, v216 offset:14336
	ds_read_b32 v197, v216 offset:17408
	ds_read_b32 v198, v216 offset:20480
	ds_read_b32 v199, v216 offset:23552
	s_mul_i32 s36, s98, 0xc00
	s_add_u32 s36, s40, s36
	s_addc_u32 s37, s41, 0
	s_waitcnt lgkmcnt(8)
	v_add_f32_e32 v217, 0, v184
	v_add_f32_e32 v217, v217, v185
	v_add_f32_e32 v217, v217, v186
	v_add_f32_e32 v217, v217, v187
	v_add_f32_e32 v217, v217, v188
	v_add_f32_e32 v217, v217, v189
	v_add_f32_e32 v217, v217, v190
	v_add_f32_e32 v217, v217, v191
	s_waitcnt lgkmcnt(0)
	v_add_f32_e32 v218, 0, v192
	v_add_f32_e32 v218, v218, v193
	v_add_f32_e32 v218, v218, v194
	v_add_f32_e32 v218, v218, v195
	v_add_f32_e32 v218, v218, v196
	v_add_f32_e32 v218, v218, v197
	v_add_f32_e32 v218, v218, v198
	v_add_f32_e32 v218, v218, v199
	global_store_dword v216, v217, s[36:37]
	v_cmp_gt_u32_e32 vcc, 0x100, v166
	s_and_saveexec_b64 s[42:43], vcc
	global_store_dword v216, v218, s[36:37] offset:2048
	s_mov_b64 exec, s[42:43]
	s_add_u32 s98, s98, s99
	s_barrier
	s_cmp_lt_u32 s98, s100
	s_cbranch_scc1 .Lpost0_tile
	s_cmp_lg_u32 s101, 0
	s_cbranch_scc1 .Lpost0_retB
.Lpost0_retA:
.LBB0_821:
	s_mov_b64 s[36:37], 0

; DI int osgpr(int v) { asm volatile("" : "+s"(v)); return v; }
; #define PHASE_BEGIN P q = p; { size_t z_ = 0; asm volatile("" : "+s"(z_)); q.ws = p.ws + z_; } unsigned char* sm = smem + osgpr(0); const int b1 = osgpr(bid); (void)sm; (void)b1;
; DI void post_phase(const P& p, int l, unsigned char* smem, int t0, int t1, int bstart, int bstride) {
;     ...
;     for (int rt = t0 + osgpr(bstart); rt < t1; rt += bstride) {
; __global__ __launch_bounds__(512, 2) void mega(P p) {
;     ...
;             { PHASE_BEGIN post_phase(q, 0, sm, NLAT / 16, NROW / 16, b1, nb); }
.LBB0_890:
	s_or_b64 exec, exec, s[0:1]
	s_mov_b64 s[0:1], 0
	s_mov_b32 s3, s19
	v_readlane_b32 s2, v253, 0
	s_waitcnt lgkmcnt(0)
	s_barrier
	v_mov_b32_e32 v0, v166
	s_cmp_gt_i32 s2, 63
	s_cbranch_scc1 .LBB0_903
	s_add_u32 s98, s2, 0x200
	v_readlane_b32 s99, v254, 28
	s_movk_i32 s100, 0x240
	s_mov_b32 s101, 1
	s_branch .Lpost0
.Lpost0_retB:
.LBB0_903:
	s_waitcnt vmcnt(0)
	s_barrier
	s_mov_b64 s[0:1], exec
	v_readlane_b32 s2, v253, 1
	v_readlane_b32 s3, v253, 2
	s_and_b64 s[2:3], s[0:1], s[2:3]
	s_mov_b64 exec, s[2:3]
	s_cbranch_execz .LBB0_172
	v_readlane_b32 s2, v254, 32
	s_waitcnt vmcnt(0) expcnt(0) lgkmcnt(0)
	s_nop 0
	v_mov_b32_e32 v0, s2
	ds_read_b32 v2, v0
	v_readlane_b32 s2, v254, 33
	s_waitcnt lgkmcnt(0)
	v_cmp_ne_u32_e32 vcc, 0, v2
	v_mov_b32_e32 v0, s2
	ds_read_b32 v0, v0
	s_cbranch_vccnz .LBB0_919
	s_mov_b32 s2, 1
	s_branch .LBB0_907

; __global__ __launch_bounds__(512, 2) void mega(P p) {
	.amdhsa_kernel _Z4mega1P
		.amdhsa_group_segment_fixed_size 0
		.amdhsa_private_segment_fixed_size 0
		.amdhsa_kernarg_size 424
		.amdhsa_user_sgpr_count 2
		.amdhsa_user_sgpr_dispatch_ptr 0
		.amdhsa_user_sgpr_queue_ptr 0
		.amdhsa_user_sgpr_kernarg_segment_ptr 1
		.amdhsa_user_sgpr_dispatch_id 0
		.amdhsa_user_sgpr_kernarg_preload_length 0
		.amdhsa_user_sgpr_kernarg_preload_offset 0
		.amdhsa_user_sgpr_private_segment_size 0
		.amdhsa_uses_dynamic_stack 0
		.amdhsa_enable_private_segment 0
		.amdhsa_system_sgpr_workgroup_id_x 1
		.amdhsa_system_sgpr_workgroup_id_y 0
		.amdhsa_system_sgpr_workgroup_id_z 0
		.amdhsa_system_sgpr_workgroup_info 0
		.amdhsa_system_vgpr_workitem_id 2
		.amdhsa_next_free_vgpr 255
		.amdhsa_next_free_sgpr 102
		.amdhsa_accum_offset 256
		.amdhsa_reserve_vcc 1
		.amdhsa_float_round_mode_32 0
		.amdhsa_float_round_mode_16_64 0
		.amdhsa_float_denorm_mode_32 3
		.amdhsa_float_denorm_mode_16_64 3
		.amdhsa_dx10_clamp 1
		.amdhsa_ieee_mode 1
		.amdhsa_fp16_overflow 0
		.amdhsa_tg_split 0
		.amdhsa_exception_fp_ieee_invalid_op 0
		.amdhsa_exception_fp_denorm_src 0
		.amdhsa_exception_fp_ieee_div_zero 0
		.amdhsa_exception_fp_ieee_overflow 0
		.amdhsa_exception_fp_ieee_underflow 0
		.amdhsa_exception_fp_ieee_inexact 0
		.amdhsa_exception_int_div_zero 0
	.end_amdhsa_kernel

; __global__ __launch_bounds__(512, 2) void mega(P p) {
amdhsa.kernels:
  - .agpr_count:     0
    .args:
      - .offset:         0
        .size:           168
        .value_kind:     by_value
      - .offset:         168
        .size:           4
        .value_kind:     hidden_block_count_x
      - .offset:         172
        .size:           4
        .value_kind:     hidden_block_count_y
      - .offset:         176
        .size:           4
        .value_kind:     hidden_block_count_z
      - .offset:         180
        .size:           2
        .value_kind:     hidden_group_size_x
      - .offset:         182
        .size:           2
        .value_kind:     hidden_group_size_y
      - .offset:         184
        .size:           2
        .value_kind:     hidden_group_size_z
      - .offset:         186
        .size:           2
        .value_kind:     hidden_remainder_x
      - .offset:         188
        .size:           2
        .value_kind:     hidden_remainder_y
      - .offset:         190
        .size:           2
        .value_kind:     hidden_remainder_z
      - .offset:         208
        .size:           8
        .value_kind:     hidden_global_offset_x
      - .offset:         216
        .size:           8
        .value_kind:     hidden_global_offset_y
      - .offset:         224
        .size:           8
        .value_kind:     hidden_global_offset_z
      - .offset:         232
        .size:           2
        .value_kind:     hidden_grid_dims
      - .offset:         256
        .size:           8
        .value_kind:     hidden_multigrid_sync_arg
      - .offset:         288
        .size:           4
        .value_kind:     hidden_dynamic_lds_size
    .group_segment_fixed_size: 0
    .kernarg_segment_align: 8
    .kernarg_segment_size: 424
    .language:       OpenCL C
    .language_version:
      - 2
      - 0
    .max_flat_workgroup_size: 512
    .name:           _Z4mega1P
    .private_segment_fixed_size: 0
    .sgpr_count:     108
    .sgpr_spill_count: 144
    .symbol:         _Z4mega1P.kd
    .uniform_work_group_size: 1
    .uses_dynamic_stack: false
    .vgpr_count:     255
    .vgpr_spill_count: 0
    .wavefront_size: 64
